# GEMM K-loops: loop-edge SALU block (pointer advance, counter, exit test) rotated in front of the iteration's last barrier (back-edge rotation)
# speedup vs baseline: 1.0125x; 1.0003x over previous
; #define PG8_STAGE(bufoff, gbase, voff) do { _Pragma("unroll") for (int _i = 0; _i < 2; ++_i) \
;         __builtin_amdgcn_global_load_lds((const unsigned*)((const char*)(gbase) + _i * rdelta + (voff)), (LAS unsigned*)(lds + (bufoff) + ldsw + _i * 8192), 16, 0, 0); } while (0)
; #define PG8_LDA(dst, b, h) do { _Pragma("unroll") for (int m = 0; m < 4; ++m) _Pragma("unroll") for (int k = 0; k < 2; ++k) dst[m][k] = *(const LAS bf16x8*)(lds + PG8_SA(b, h) + aoff + m * 2048 + k * 1024); } while (0)
; #define PG8_LDB(dst, b, h) do { _Pragma("unroll") for (int n = 0; n < 2; ++n) _Pragma("unroll") for (int k = 0; k < 2; ++k) dst[n][k] = *(const LAS bf16x8*)(lds + PG8_SB(b, h) + boff + n * 2048 + k * 1024); } while (0)
; #define PG8_MMA(ai, bj, At, Bt) do { __builtin_amdgcn_s_setprio(1); _Pragma("unroll") for (int m = 0; m < 4; ++m) _Pragma("unroll") for (int n = 0; n < 2; ++n) _Pragma("unroll") for (int k = 0; k < 2; ++k) \
;         acc[ai][bj][m][n] = __builtin_amdgcn_mfma_f32_16x16x32_bf16(Bt[n][k], At[m][k], acc[ai][bj][m][n], 0, 0, 0); __builtin_amdgcn_s_setprio(0); } while (0)
; #define PG8_WAIT_V(n) asm volatile("s_waitcnt vmcnt(" #n ")" ::: "memory")
; #define PG8_WAIT_L(n) asm volatile("s_waitcnt lgkmcnt(" #n ")" ::: "memory")
; template <class Epi, class Sched, bool ALIGN_EPI, bool SP2>
; __device__ __forceinline__ void gemm_phase(LAS unsigned char* lds, const Gemm g, const Sched& S, const Epi& E) {
;     ...
;         for (int t = 0; t < nt; t += 2) {
;             if constexpr (Epi::HOOK) { if (t == Epi::T1 || t == Epi::T2) E.hook(acc, ui, t, wr, fr); }
;             const bool last = (t == nt - 2);
;             const char* a1 = cA + (size_t)(t + 1) * kstep;
;             const char* a2 = last ? nA : cA + (size_t)(t + 2) * kstep; const char* b2 = last ? nB : cB + (size_t)(t + 2) * kstep;
;             const char* a3 = a2 + kstep; const char* b3 = b2 + kstep;
;             PG8_LDB(B0, 0, 0); PG8_LDB(B1, 0, 1); PG8_SCHED; PG8_LDA(At, 0, 0); PG8_STAGE(PG8_SA(1, 1), a1 + hstep, voffA);
;             PG8_WAIT_V(8); PG8_WAIT_L(0); PG8_BAR; PG8_MMA(0, 0, At, B0); PG8_MMA(0, 1, At, B1); PG8_BAR; PG8_SCHED;
;             PG8_LDA(At, 0, 1); PG8_STAGE(PG8_SB(0, 0), b2, voffB); PG8_STAGE(PG8_SB(0, 1), b2 + hstep, voffB); PG8_STAGE(PG8_SA(0, 0), a2, voffA);
;             PG8_WAIT_V(8); PG8_WAIT_L(0); PG8_BAR; PG8_MMA(1, 0, At, B0); PG8_MMA(1, 1, At, B1); PG8_BAR; PG8_SCHED;
.LBB0_194:
	s_add_i32 s18, s4, 2
	s_add_u32 s14, s6, 0x80
	s_addc_u32 s15, s7, 0
	s_add_i32 s19, 0, 0x10000
	s_cmp_eq_u32 s96, s4
	s_cselect_b32 s15, s69, s15
	s_cselect_b32 s14, s68, s14
	v_add_u32_e32 v128, s19, v145
	s_cselect_b32 s51, s71, s17
	s_cselect_b32 s50, s70, s16
	s_add_i32 s4, 0, 0x14000
	ds_read_b128 v[136:139], v128
	ds_read_b128 v[152:155], v128 offset:1024
	ds_read_b128 v[156:159], v128 offset:2048
	ds_read_b128 v[160:163], v128 offset:3072
	v_add_u32_e32 v128, s4, v145
	ds_read_b128 v[164:167], v128
	ds_read_b128 v[172:175], v128 offset:1024
	ds_read_b128 v[176:179], v128 offset:2048
	ds_read_b128 v[180:183], v128 offset:3072
	v_lshl_add_u64 v[168:169], s[6:7], 0, v[148:149]
	s_add_i32 m0, s37, 0xc000
	ds_read_b128 v[208:211], v171
	ds_read_b128 v[212:215], v171 offset:1024
	ds_read_b128 v[216:219], v171 offset:2048
	ds_read_b128 v[220:223], v171 offset:3072
	ds_read_b128 v[224:227], v171 offset:4096
	ds_read_b128 v[228:231], v171 offset:5120
	ds_read_b128 v[232:235], v171 offset:6144
	ds_read_b128 v[236:239], v171 offset:7168
	global_load_lds_dwordx4 v[168:169], off
	v_lshl_add_u64 v[168:169], s[6:7], 0, v[150:151]
	s_add_i32 m0, s37, 0xe000
	s_nop 0
	global_load_lds_dwordx4 v[168:169], off
	s_waitcnt vmcnt(8)
	s_waitcnt lgkmcnt(0)
	s_barrier
	s_setprio 1
	s_waitcnt lgkmcnt(0)
	v_mfma_f32_16x16x32_bf16 v[120:123], v[136:139], v[208:211], v[120:123]
	v_mfma_f32_16x16x32_bf16 v[124:127], v[156:159], v[208:211], v[124:127]
	v_mfma_f32_16x16x32_bf16 v[108:111], v[136:139], v[216:219], v[108:111]
	v_mfma_f32_16x16x32_bf16 v[104:107], v[156:159], v[216:219], v[104:107]
	v_mfma_f32_16x16x32_bf16 v[92:95], v[136:139], v[224:227], v[92:95]
	v_mfma_f32_16x16x32_bf16 v[88:91], v[156:159], v[224:227], v[88:91]
	v_mfma_f32_16x16x32_bf16 v[76:79], v[136:139], v[232:235], v[76:79]
	v_mfma_f32_16x16x32_bf16 v[72:75], v[156:159], v[232:235], v[72:75]
	v_mfma_f32_16x16x32_bf16 v[120:123], v[152:155], v[212:215], v[120:123]
	v_mfma_f32_16x16x32_bf16 v[124:127], v[160:163], v[212:215], v[124:127]
	v_mfma_f32_16x16x32_bf16 v[108:111], v[152:155], v[220:223], v[108:111]
	v_mfma_f32_16x16x32_bf16 v[104:107], v[160:163], v[220:223], v[104:107]
	v_mfma_f32_16x16x32_bf16 v[92:95], v[152:155], v[228:231], v[92:95]
	v_mfma_f32_16x16x32_bf16 v[88:91], v[160:163], v[228:231], v[88:91]
	v_mfma_f32_16x16x32_bf16 v[76:79], v[152:155], v[236:239], v[76:79]
	v_mfma_f32_16x16x32_bf16 v[72:75], v[160:163], v[236:239], v[72:75]
	s_setprio 0
	s_setprio 1
	v_mfma_f32_16x16x32_bf16 v[116:119], v[164:167], v[208:211], v[116:119]
	v_mfma_f32_16x16x32_bf16 v[112:115], v[176:179], v[208:211], v[112:115]
	v_mfma_f32_16x16x32_bf16 v[100:103], v[164:167], v[216:219], v[100:103]
	v_mfma_f32_16x16x32_bf16 v[96:99], v[176:179], v[216:219], v[96:99]
	v_mfma_f32_16x16x32_bf16 v[84:87], v[164:167], v[224:227], v[84:87]
	v_mfma_f32_16x16x32_bf16 v[80:83], v[176:179], v[224:227], v[80:83]
	v_mfma_f32_16x16x32_bf16 v[68:71], v[164:167], v[232:235], v[68:71]
	v_mfma_f32_16x16x32_bf16 v[64:67], v[176:179], v[232:235], v[64:67]
	v_mfma_f32_16x16x32_bf16 v[116:119], v[172:175], v[212:215], v[116:119]
	v_mfma_f32_16x16x32_bf16 v[112:115], v[180:183], v[212:215], v[112:115]
	v_mfma_f32_16x16x32_bf16 v[100:103], v[172:175], v[220:223], v[100:103]
	v_mfma_f32_16x16x32_bf16 v[96:99], v[180:183], v[220:223], v[96:99]
	v_mfma_f32_16x16x32_bf16 v[84:87], v[172:175], v[228:231], v[84:87]
	v_mfma_f32_16x16x32_bf16 v[80:83], v[180:183], v[228:231], v[80:83]
	v_mfma_f32_16x16x32_bf16 v[68:71], v[172:175], v[236:239], v[68:71]
	v_mfma_f32_16x16x32_bf16 v[64:67], v[180:183], v[236:239], v[64:67]
	s_setprio 0
	s_barrier
	s_add_i32 s19, s19, s36
	v_lshl_add_u64 v[168:169], s[50:51], 0, v[130:131]
	s_mov_b32 m0, s19
	ds_read_b128 v[208:211], v171 offset:16384
	ds_read_b128 v[212:215], v171 offset:17408
	ds_read_b128 v[216:219], v171 offset:18432
	ds_read_b128 v[220:223], v171 offset:19456
	ds_read_b128 v[224:227], v171 offset:20480
	ds_read_b128 v[228:231], v171 offset:21504
	ds_read_b128 v[232:235], v171 offset:22528
	ds_read_b128 v[236:239], v171 offset:23552
	global_load_lds_dwordx4 v[168:169], off
	s_add_i32 m0, s19, 0x2000
	s_add_u32 s50, s50, s12
	v_lshl_add_u64 v[240:241], v[168:169], 0, s[10:11]
	s_addc_u32 s51, s51, s13
	s_add_i32 s4, s4, s36
	global_load_lds_dwordx4 v[240:241], off
	v_lshl_add_u64 v[242:243], s[50:51], 0, v[130:131]
	s_mov_b32 m0, s4
	v_lshl_add_u64 v[244:245], v[242:243], 0, s[10:11]
	global_load_lds_dwordx4 v[242:243], off
	s_add_i32 m0, s4, 0x2000
	v_lshl_add_u64 v[246:247], s[14:15], 0, v[140:141]
	global_load_lds_dwordx4 v[244:245], off
	s_mov_b32 m0, s37
	v_lshl_add_u64 v[248:249], v[246:247], 0, s[10:11]
	global_load_lds_dwordx4 v[246:247], off
	s_mov_b32 m0, s90
	s_nop 0
	global_load_lds_dwordx4 v[248:249], off
	s_waitcnt vmcnt(8)
	s_waitcnt lgkmcnt(0)
	s_barrier
; #define PG8_STAGE(bufoff, gbase, voff) do { _Pragma("unroll") for (int _i = 0; _i < 2; ++_i) \
;         __builtin_amdgcn_global_load_lds((const unsigned*)((const char*)(gbase) + _i * rdelta + (voff)), (LAS unsigned*)(lds + (bufoff) + ldsw + _i * 8192), 16, 0, 0); } while (0)
; #define PG8_LDA(dst, b, h) do { _Pragma("unroll") for (int m = 0; m < 4; ++m) _Pragma("unroll") for (int k = 0; k < 2; ++k) dst[m][k] = *(const LAS bf16x8*)(lds + PG8_SA(b, h) + aoff + m * 2048 + k * 1024); } while (0)
; #define PG8_LDB(dst, b, h) do { _Pragma("unroll") for (int n = 0; n < 2; ++n) _Pragma("unroll") for (int k = 0; k < 2; ++k) dst[n][k] = *(const LAS bf16x8*)(lds + PG8_SB(b, h) + boff + n * 2048 + k * 1024); } while (0)
; #define PG8_MMA(ai, bj, At, Bt) do { __builtin_amdgcn_s_setprio(1); _Pragma("unroll") for (int m = 0; m < 4; ++m) _Pragma("unroll") for (int n = 0; n < 2; ++n) _Pragma("unroll") for (int k = 0; k < 2; ++k) \
;         acc[ai][bj][m][n] = __builtin_amdgcn_mfma_f32_16x16x32_bf16(Bt[n][k], At[m][k], acc[ai][bj][m][n], 0, 0, 0); __builtin_amdgcn_s_setprio(0); } while (0)
; #define PG8_WAIT_V(n) asm volatile("s_waitcnt vmcnt(" #n ")" ::: "memory")
; #define PG8_WAIT_L(n) asm volatile("s_waitcnt lgkmcnt(" #n ")" ::: "memory")
; #define PG8_BAR __builtin_amdgcn_s_barrier()
; #define PG8_SCHED __builtin_amdgcn_sched_barrier(0)
; template <class Epi, class Sched, bool ALIGN_EPI, bool SP2>
; __device__ __forceinline__ void gemm_phase(LAS unsigned char* lds, const Gemm g, const Sched& S, const Epi& E) {
;     ...
;             PG8_WAIT_V(8); PG8_WAIT_L(0); PG8_BAR; PG8_MMA(1, 0, At, B0); PG8_MMA(1, 1, At, B1); PG8_BAR; PG8_SCHED;
;             PG8_LDB(B0, 1, 0); PG8_LDB(B1, 1, 1); PG8_SCHED; PG8_LDA(At, 1, 0); PG8_STAGE(PG8_SA(0, 1), a2 + hstep, voffA);
;             PG8_WAIT_V(8); PG8_WAIT_L(0); PG8_BAR; PG8_MMA(0, 0, At, B0); PG8_MMA(0, 1, At, B1); PG8_BAR; PG8_SCHED;
	s_setprio 1
	s_waitcnt lgkmcnt(0)
	v_mfma_f32_16x16x32_bf16 v[60:63], v[136:139], v[208:211], v[60:63]
	v_mfma_f32_16x16x32_bf16 v[56:59], v[156:159], v[208:211], v[56:59]
	v_mfma_f32_16x16x32_bf16 v[44:47], v[136:139], v[216:219], v[44:47]
	v_mfma_f32_16x16x32_bf16 v[40:43], v[156:159], v[216:219], v[40:43]
	v_mfma_f32_16x16x32_bf16 v[28:31], v[136:139], v[224:227], v[28:31]
	v_mfma_f32_16x16x32_bf16 v[24:27], v[156:159], v[224:227], v[24:27]
	v_mfma_f32_16x16x32_bf16 v[12:15], v[136:139], v[232:235], v[12:15]
	v_mfma_f32_16x16x32_bf16 v[8:11], v[156:159], v[232:235], v[8:11]
	v_mfma_f32_16x16x32_bf16 v[60:63], v[152:155], v[212:215], v[60:63]
	v_mfma_f32_16x16x32_bf16 v[56:59], v[160:163], v[212:215], v[56:59]
	v_mfma_f32_16x16x32_bf16 v[44:47], v[152:155], v[220:223], v[44:47]
	v_mfma_f32_16x16x32_bf16 v[40:43], v[160:163], v[220:223], v[40:43]
	v_mfma_f32_16x16x32_bf16 v[28:31], v[152:155], v[228:231], v[28:31]
	v_mfma_f32_16x16x32_bf16 v[24:27], v[160:163], v[228:231], v[24:27]
	v_mfma_f32_16x16x32_bf16 v[12:15], v[152:155], v[236:239], v[12:15]
	v_mfma_f32_16x16x32_bf16 v[8:11], v[160:163], v[236:239], v[8:11]
	s_setprio 0
	s_setprio 1
	v_mfma_f32_16x16x32_bf16 v[52:55], v[164:167], v[208:211], v[52:55]
	v_mfma_f32_16x16x32_bf16 v[48:51], v[176:179], v[208:211], v[48:51]
	v_mfma_f32_16x16x32_bf16 v[36:39], v[164:167], v[216:219], v[36:39]
	v_mfma_f32_16x16x32_bf16 v[32:35], v[176:179], v[216:219], v[32:35]
	v_mfma_f32_16x16x32_bf16 v[20:23], v[164:167], v[224:227], v[20:23]
	v_mfma_f32_16x16x32_bf16 v[16:19], v[176:179], v[224:227], v[16:19]
	v_mfma_f32_16x16x32_bf16 v[4:7], v[164:167], v[232:235], v[4:7]
	v_mfma_f32_16x16x32_bf16 v[0:3], v[176:179], v[232:235], v[0:3]
	v_mfma_f32_16x16x32_bf16 v[52:55], v[172:175], v[212:215], v[52:55]
	v_mfma_f32_16x16x32_bf16 v[48:51], v[180:183], v[212:215], v[48:51]
	v_mfma_f32_16x16x32_bf16 v[36:39], v[172:175], v[220:223], v[36:39]
	v_mfma_f32_16x16x32_bf16 v[32:35], v[180:183], v[220:223], v[32:35]
	v_mfma_f32_16x16x32_bf16 v[20:23], v[172:175], v[228:231], v[20:23]
	v_mfma_f32_16x16x32_bf16 v[16:19], v[180:183], v[228:231], v[16:19]
	v_mfma_f32_16x16x32_bf16 v[4:7], v[172:175], v[236:239], v[4:7]
	v_mfma_f32_16x16x32_bf16 v[0:3], v[180:183], v[236:239], v[0:3]
	s_setprio 0
	s_barrier
	s_add_i32 s4, 0, 0x18000
	v_add_u32_e32 v128, s4, v145
	s_add_i32 s19, 0, 0x1c000
	ds_read_b128 v[136:139], v128
	ds_read_b128 v[152:155], v128 offset:1024
	ds_read_b128 v[156:159], v128 offset:2048
	ds_read_b128 v[160:163], v128 offset:3072
	v_add_u32_e32 v128, s19, v145
	ds_read_b128 v[164:167], v128
	ds_read_b128 v[172:175], v128 offset:1024
	ds_read_b128 v[176:179], v128 offset:2048
	ds_read_b128 v[180:183], v128 offset:3072
	s_add_u32 s14, s14, s12
	s_addc_u32 s15, s15, s13
	s_mov_b32 m0, s91
	v_lshl_add_u64 v[250:251], s[14:15], 0, v[140:141]
	ds_read_b128 v[208:211], v171 offset:32768
	ds_read_b128 v[212:215], v171 offset:33792
	ds_read_b128 v[216:219], v171 offset:34816
	ds_read_b128 v[220:223], v171 offset:35840
	ds_read_b128 v[224:227], v171 offset:36864
	ds_read_b128 v[228:231], v171 offset:37888
	ds_read_b128 v[232:235], v171 offset:38912
	ds_read_b128 v[236:239], v171 offset:39936
	global_load_lds_dwordx4 v[250:251], off
	v_lshl_add_u64 v[250:251], v[250:251], 0, s[10:11]
	s_mov_b32 m0, s92
	s_nop 0
	global_load_lds_dwordx4 v[250:251], off
	s_waitcnt vmcnt(8)
	s_waitcnt lgkmcnt(0)
	s_barrier
	s_setprio 1
	s_waitcnt lgkmcnt(0)
	v_mfma_f32_16x16x32_bf16 v[120:123], v[136:139], v[208:211], v[120:123]
	v_mfma_f32_16x16x32_bf16 v[124:127], v[156:159], v[208:211], v[124:127]
	v_mfma_f32_16x16x32_bf16 v[108:111], v[136:139], v[216:219], v[108:111]
	v_mfma_f32_16x16x32_bf16 v[104:107], v[156:159], v[216:219], v[104:107]
	v_mfma_f32_16x16x32_bf16 v[92:95], v[136:139], v[224:227], v[92:95]
	v_mfma_f32_16x16x32_bf16 v[88:91], v[156:159], v[224:227], v[88:91]
	v_mfma_f32_16x16x32_bf16 v[76:79], v[136:139], v[232:235], v[76:79]
	v_mfma_f32_16x16x32_bf16 v[72:75], v[156:159], v[232:235], v[72:75]
	v_mfma_f32_16x16x32_bf16 v[120:123], v[152:155], v[212:215], v[120:123]
	v_mfma_f32_16x16x32_bf16 v[124:127], v[160:163], v[212:215], v[124:127]
	v_mfma_f32_16x16x32_bf16 v[108:111], v[152:155], v[220:223], v[108:111]
	v_mfma_f32_16x16x32_bf16 v[104:107], v[160:163], v[220:223], v[104:107]
	v_mfma_f32_16x16x32_bf16 v[92:95], v[152:155], v[228:231], v[92:95]
	v_mfma_f32_16x16x32_bf16 v[88:91], v[160:163], v[228:231], v[88:91]
	v_mfma_f32_16x16x32_bf16 v[76:79], v[152:155], v[236:239], v[76:79]
	v_mfma_f32_16x16x32_bf16 v[72:75], v[160:163], v[236:239], v[72:75]
	s_setprio 0
	s_setprio 1
	v_mfma_f32_16x16x32_bf16 v[116:119], v[164:167], v[208:211], v[116:119]
	v_mfma_f32_16x16x32_bf16 v[112:115], v[176:179], v[208:211], v[112:115]
	v_mfma_f32_16x16x32_bf16 v[100:103], v[164:167], v[216:219], v[100:103]
	v_mfma_f32_16x16x32_bf16 v[96:99], v[176:179], v[216:219], v[96:99]
	v_mfma_f32_16x16x32_bf16 v[84:87], v[164:167], v[224:227], v[84:87]
	v_mfma_f32_16x16x32_bf16 v[80:83], v[176:179], v[224:227], v[80:83]
	v_mfma_f32_16x16x32_bf16 v[68:71], v[164:167], v[232:235], v[68:71]
	v_mfma_f32_16x16x32_bf16 v[64:67], v[176:179], v[232:235], v[64:67]
	v_mfma_f32_16x16x32_bf16 v[116:119], v[172:175], v[212:215], v[116:119]
	v_mfma_f32_16x16x32_bf16 v[112:115], v[180:183], v[212:215], v[112:115]
	v_mfma_f32_16x16x32_bf16 v[100:103], v[172:175], v[220:223], v[100:103]
	v_mfma_f32_16x16x32_bf16 v[96:99], v[180:183], v[220:223], v[96:99]
	v_mfma_f32_16x16x32_bf16 v[84:87], v[172:175], v[228:231], v[84:87]
	v_mfma_f32_16x16x32_bf16 v[80:83], v[180:183], v[228:231], v[80:83]
	v_mfma_f32_16x16x32_bf16 v[68:71], v[172:175], v[236:239], v[68:71]
	v_mfma_f32_16x16x32_bf16 v[64:67], v[180:183], v[236:239], v[64:67]
	s_setprio 0
	s_barrier
; #define PG8_STAGE(bufoff, gbase, voff) do { _Pragma("unroll") for (int _i = 0; _i < 2; ++_i) \
;         __builtin_amdgcn_global_load_lds((const unsigned*)((const char*)(gbase) + _i * rdelta + (voff)), (LAS unsigned*)(lds + (bufoff) + ldsw + _i * 8192), 16, 0, 0); } while (0)
; #define PG8_LDA(dst, b, h) do { _Pragma("unroll") for (int m = 0; m < 4; ++m) _Pragma("unroll") for (int k = 0; k < 2; ++k) dst[m][k] = *(const LAS bf16x8*)(lds + PG8_SA(b, h) + aoff + m * 2048 + k * 1024); } while (0)
; #define PG8_MMA(ai, bj, At, Bt) do { __builtin_amdgcn_s_setprio(1); _Pragma("unroll") for (int m = 0; m < 4; ++m) _Pragma("unroll") for (int n = 0; n < 2; ++n) _Pragma("unroll") for (int k = 0; k < 2; ++k) \
;         acc[ai][bj][m][n] = __builtin_amdgcn_mfma_f32_16x16x32_bf16(Bt[n][k], At[m][k], acc[ai][bj][m][n], 0, 0, 0); __builtin_amdgcn_s_setprio(0); } while (0)
; #define PG8_WAIT_V(n) asm volatile("s_waitcnt vmcnt(" #n ")" ::: "memory")
; #define PG8_WAIT_L(n) asm volatile("s_waitcnt lgkmcnt(" #n ")" ::: "memory")
; #define PG8_BAR __builtin_amdgcn_s_barrier()
; #define PG8_SCHED __builtin_amdgcn_sched_barrier(0)
; template <class Epi, class Sched, bool ALIGN_EPI, bool SP2>
; __device__ __forceinline__ void gemm_phase(LAS unsigned char* lds, const Gemm g, const Sched& S, const Epi& E) {
;     ...
;             PG8_LDA(At, 1, 1); PG8_STAGE(PG8_SB(1, 0), b3, voffB); PG8_STAGE(PG8_SB(1, 1), b3 + hstep, voffB); PG8_STAGE(PG8_SA(1, 0), a3, voffA);
;             PG8_WAIT_V(8); PG8_WAIT_L(0); PG8_BAR; PG8_MMA(1, 0, At, B0); PG8_MMA(1, 1, At, B1); PG8_BAR; PG8_SCHED;
;         }
	s_add_i32 s4, s4, s36
	v_lshl_add_u64 v[168:169], v[168:169], 0, s[30:31]
	s_mov_b32 m0, s4
	ds_read_b128 v[208:211], v171 offset:49152
	ds_read_b128 v[212:215], v171 offset:50176
	ds_read_b128 v[216:219], v171 offset:51200
	ds_read_b128 v[220:223], v171 offset:52224
	ds_read_b128 v[224:227], v171 offset:53248
	ds_read_b128 v[228:231], v171 offset:54272
	ds_read_b128 v[232:235], v171 offset:55296
	ds_read_b128 v[236:239], v171 offset:56320
	global_load_lds_dwordx4 v[168:169], off
	v_lshl_add_u64 v[168:169], v[240:241], 0, s[30:31]
	s_add_i32 m0, s4, 0x2000
	s_add_i32 s4, s19, s36
	global_load_lds_dwordx4 v[168:169], off
	v_lshl_add_u64 v[168:169], v[242:243], 0, s[30:31]
	s_mov_b32 m0, s4
	s_nop 0
	global_load_lds_dwordx4 v[168:169], off
	v_lshl_add_u64 v[168:169], v[244:245], 0, s[30:31]
	s_add_i32 m0, s4, 0x2000
	s_nop 0
	global_load_lds_dwordx4 v[168:169], off
	v_lshl_add_u64 v[168:169], v[246:247], 0, s[30:31]
	s_mov_b32 m0, s93
	s_nop 0
	global_load_lds_dwordx4 v[168:169], off
	v_lshl_add_u64 v[168:169], v[248:249], 0, s[30:31]
	s_mov_b32 m0, s94
	s_nop 0
	global_load_lds_dwordx4 v[168:169], off
	s_waitcnt vmcnt(8)
	s_waitcnt lgkmcnt(0)
	s_barrier
	s_setprio 1
	s_waitcnt lgkmcnt(0)
	v_mfma_f32_16x16x32_bf16 v[60:63], v[136:139], v[208:211], v[60:63]
	v_mfma_f32_16x16x32_bf16 v[56:59], v[156:159], v[208:211], v[56:59]
	v_mfma_f32_16x16x32_bf16 v[44:47], v[136:139], v[216:219], v[44:47]
	v_mfma_f32_16x16x32_bf16 v[40:43], v[156:159], v[216:219], v[40:43]
	v_mfma_f32_16x16x32_bf16 v[28:31], v[136:139], v[224:227], v[28:31]
	v_mfma_f32_16x16x32_bf16 v[24:27], v[156:159], v[224:227], v[24:27]
	v_mfma_f32_16x16x32_bf16 v[12:15], v[136:139], v[232:235], v[12:15]
	v_mfma_f32_16x16x32_bf16 v[8:11], v[156:159], v[232:235], v[8:11]
	v_mfma_f32_16x16x32_bf16 v[60:63], v[152:155], v[212:215], v[60:63]
	v_mfma_f32_16x16x32_bf16 v[56:59], v[160:163], v[212:215], v[56:59]
	v_mfma_f32_16x16x32_bf16 v[44:47], v[152:155], v[220:223], v[44:47]
	v_mfma_f32_16x16x32_bf16 v[40:43], v[160:163], v[220:223], v[40:43]
	v_mfma_f32_16x16x32_bf16 v[28:31], v[152:155], v[228:231], v[28:31]
	v_mfma_f32_16x16x32_bf16 v[24:27], v[160:163], v[228:231], v[24:27]
	v_mfma_f32_16x16x32_bf16 v[12:15], v[152:155], v[236:239], v[12:15]
	v_mfma_f32_16x16x32_bf16 v[8:11], v[160:163], v[236:239], v[8:11]
	s_setprio 0
	s_setprio 1
	v_mfma_f32_16x16x32_bf16 v[52:55], v[164:167], v[208:211], v[52:55]
	v_mfma_f32_16x16x32_bf16 v[48:51], v[176:179], v[208:211], v[48:51]
	v_mfma_f32_16x16x32_bf16 v[36:39], v[164:167], v[216:219], v[36:39]
	v_mfma_f32_16x16x32_bf16 v[32:35], v[176:179], v[216:219], v[32:35]
	v_mfma_f32_16x16x32_bf16 v[20:23], v[164:167], v[224:227], v[20:23]
	v_mfma_f32_16x16x32_bf16 v[16:19], v[176:179], v[224:227], v[16:19]
	v_mfma_f32_16x16x32_bf16 v[4:7], v[164:167], v[232:235], v[4:7]
	v_mfma_f32_16x16x32_bf16 v[0:3], v[176:179], v[232:235], v[0:3]
	v_mfma_f32_16x16x32_bf16 v[52:55], v[172:175], v[212:215], v[52:55]
	v_mfma_f32_16x16x32_bf16 v[48:51], v[180:183], v[212:215], v[48:51]
	v_mfma_f32_16x16x32_bf16 v[36:39], v[172:175], v[220:223], v[36:39]
	v_mfma_f32_16x16x32_bf16 v[32:35], v[180:183], v[220:223], v[32:35]
	v_mfma_f32_16x16x32_bf16 v[20:23], v[172:175], v[228:231], v[20:23]
	v_mfma_f32_16x16x32_bf16 v[16:19], v[180:183], v[228:231], v[16:19]
	v_mfma_f32_16x16x32_bf16 v[4:7], v[172:175], v[236:239], v[4:7]
	v_mfma_f32_16x16x32_bf16 v[0:3], v[180:183], v[236:239], v[0:3]
	s_setprio 0
	s_add_u32 s6, s6, 0x100
	s_addc_u32 s7, s7, 0
	s_add_u32 s16, s16, 0x100
	s_addc_u32 s17, s17, 0
	s_cmp_ge_i32 s18, s95
	s_mov_b32 s4, s18
	s_barrier
	s_cbranch_scc0 .LBB0_194

; #define PG8_STAGE(bufoff, gbase, voff) do { _Pragma("unroll") for (int _i = 0; _i < 2; ++_i) \
;         __builtin_amdgcn_global_load_lds((const unsigned*)((const char*)(gbase) + _i * rdelta + (voff)), (LAS unsigned*)(lds + (bufoff) + ldsw + _i * 8192), 16, 0, 0); } while (0)
; #define PG8_LDA(dst, b, h) do { _Pragma("unroll") for (int m = 0; m < 4; ++m) _Pragma("unroll") for (int k = 0; k < 2; ++k) dst[m][k] = *(const LAS bf16x8*)(lds + PG8_SA(b, h) + aoff + m * 2048 + k * 1024); } while (0)
; #define PG8_LDB(dst, b, h) do { _Pragma("unroll") for (int n = 0; n < 2; ++n) _Pragma("unroll") for (int k = 0; k < 2; ++k) dst[n][k] = *(const LAS bf16x8*)(lds + PG8_SB(b, h) + boff + n * 2048 + k * 1024); } while (0)
; #define PG8_MMA(ai, bj, At, Bt) do { __builtin_amdgcn_s_setprio(1); _Pragma("unroll") for (int m = 0; m < 4; ++m) _Pragma("unroll") for (int n = 0; n < 2; ++n) _Pragma("unroll") for (int k = 0; k < 2; ++k) \
;         acc[ai][bj][m][n] = __builtin_amdgcn_mfma_f32_16x16x32_bf16(Bt[n][k], At[m][k], acc[ai][bj][m][n], 0, 0, 0); __builtin_amdgcn_s_setprio(0); } while (0)
; #define PG8_WAIT_V(n) asm volatile("s_waitcnt vmcnt(" #n ")" ::: "memory")
; #define PG8_WAIT_L(n) asm volatile("s_waitcnt lgkmcnt(" #n ")" ::: "memory")
; template <class Epi, class Sched, bool ALIGN_EPI, bool SP2>
; __device__ __forceinline__ void gemm_phase(LAS unsigned char* lds, const Gemm g, const Sched& S, const Epi& E) {
;     ...
;         for (int t = 0; t < nt; t += 2) {
;             if constexpr (Epi::HOOK) { if (t == Epi::T1 || t == Epi::T2) E.hook(acc, ui, t, wr, fr); }
;             const bool last = (t == nt - 2);
;             const char* a1 = cA + (size_t)(t + 1) * kstep;
;             const char* a2 = last ? nA : cA + (size_t)(t + 2) * kstep; const char* b2 = last ? nB : cB + (size_t)(t + 2) * kstep;
;             const char* a3 = a2 + kstep; const char* b3 = b2 + kstep;
;             PG8_LDB(B0, 0, 0); PG8_LDB(B1, 0, 1); PG8_SCHED; PG8_LDA(At, 0, 0); PG8_STAGE(PG8_SA(1, 1), a1 + hstep, voffA);
;             PG8_WAIT_V(8); PG8_WAIT_L(0); PG8_BAR; PG8_MMA(0, 0, At, B0); PG8_MMA(0, 1, At, B1); PG8_BAR; PG8_SCHED;
;             PG8_LDA(At, 0, 1); PG8_STAGE(PG8_SB(0, 0), b2, voffB); PG8_STAGE(PG8_SB(0, 1), b2 + hstep, voffB); PG8_STAGE(PG8_SA(0, 0), a2, voffA);
;             PG8_WAIT_V(8); PG8_WAIT_L(0); PG8_BAR; PG8_MMA(1, 0, At, B0); PG8_MMA(1, 1, At, B1); PG8_BAR; PG8_SCHED;
.LBB0_805:
	s_add_i32 s18, s4, 2
	s_add_u32 s14, s6, 0x80
	s_addc_u32 s15, s7, 0
	s_add_i32 s19, 0, 0x10000
	s_cmp_eq_u32 s63, s4
	s_cselect_b32 s15, s59, s15
	s_cselect_b32 s14, s58, s14
	v_add_u32_e32 v128, s19, v151
	s_cselect_b32 s69, s61, s17
	s_cselect_b32 s68, s60, s16
	s_add_i32 s4, 0, 0x14000
	ds_read_b128 v[142:145], v128
	ds_read_b128 v[146:149], v128 offset:1024
	ds_read_b128 v[154:157], v128 offset:2048
	ds_read_b128 v[158:161], v128 offset:3072
	v_add_u32_e32 v128, s4, v151
	ds_read_b128 v[162:165], v128
	ds_read_b128 v[166:169], v128 offset:1024
	ds_read_b128 v[170:173], v128 offset:2048
	ds_read_b128 v[174:177], v128 offset:3072
	v_lshl_add_u64 v[182:183], s[6:7], 0, v[138:139]
	s_add_i32 m0, s35, 0xc000
	ds_read_b128 v[178:181], v153
	ds_read_b128 v[208:211], v153 offset:1024
	ds_read_b128 v[212:215], v153 offset:2048
	ds_read_b128 v[216:219], v153 offset:3072
	ds_read_b128 v[220:223], v153 offset:4096
	ds_read_b128 v[224:227], v153 offset:5120
	ds_read_b128 v[228:231], v153 offset:6144
	ds_read_b128 v[232:235], v153 offset:7168
	global_load_lds_dwordx4 v[182:183], off
	v_lshl_add_u64 v[182:183], s[6:7], 0, v[140:141]
	s_add_i32 m0, s35, 0xe000
	s_nop 0
	global_load_lds_dwordx4 v[182:183], off
	s_waitcnt vmcnt(8)
	s_waitcnt lgkmcnt(0)
	s_barrier
	s_setprio 1
	s_waitcnt lgkmcnt(0)
	v_mfma_f32_16x16x32_bf16 v[120:123], v[142:145], v[178:181], v[120:123]
	v_mfma_f32_16x16x32_bf16 v[124:127], v[154:157], v[178:181], v[124:127]
	v_mfma_f32_16x16x32_bf16 v[108:111], v[142:145], v[212:215], v[108:111]
	v_mfma_f32_16x16x32_bf16 v[104:107], v[154:157], v[212:215], v[104:107]
	v_mfma_f32_16x16x32_bf16 v[92:95], v[142:145], v[220:223], v[92:95]
	v_mfma_f32_16x16x32_bf16 v[88:91], v[154:157], v[220:223], v[88:91]
	v_mfma_f32_16x16x32_bf16 v[76:79], v[142:145], v[228:231], v[76:79]
	v_mfma_f32_16x16x32_bf16 v[72:75], v[154:157], v[228:231], v[72:75]
	v_mfma_f32_16x16x32_bf16 v[120:123], v[146:149], v[208:211], v[120:123]
	v_mfma_f32_16x16x32_bf16 v[124:127], v[158:161], v[208:211], v[124:127]
	v_mfma_f32_16x16x32_bf16 v[108:111], v[146:149], v[216:219], v[108:111]
	v_mfma_f32_16x16x32_bf16 v[104:107], v[158:161], v[216:219], v[104:107]
	v_mfma_f32_16x16x32_bf16 v[92:95], v[146:149], v[224:227], v[92:95]
	v_mfma_f32_16x16x32_bf16 v[88:91], v[158:161], v[224:227], v[88:91]
	v_mfma_f32_16x16x32_bf16 v[76:79], v[146:149], v[232:235], v[76:79]
	v_mfma_f32_16x16x32_bf16 v[72:75], v[158:161], v[232:235], v[72:75]
	s_setprio 0
	s_setprio 1
	v_mfma_f32_16x16x32_bf16 v[116:119], v[162:165], v[178:181], v[116:119]
	v_mfma_f32_16x16x32_bf16 v[112:115], v[170:173], v[178:181], v[112:115]
	v_mfma_f32_16x16x32_bf16 v[100:103], v[162:165], v[212:215], v[100:103]
	v_mfma_f32_16x16x32_bf16 v[96:99], v[170:173], v[212:215], v[96:99]
	v_mfma_f32_16x16x32_bf16 v[84:87], v[162:165], v[220:223], v[84:87]
	v_mfma_f32_16x16x32_bf16 v[80:83], v[170:173], v[220:223], v[80:83]
	v_mfma_f32_16x16x32_bf16 v[68:71], v[162:165], v[228:231], v[68:71]
	v_mfma_f32_16x16x32_bf16 v[64:67], v[170:173], v[228:231], v[64:67]
	v_mfma_f32_16x16x32_bf16 v[116:119], v[166:169], v[208:211], v[116:119]
	v_mfma_f32_16x16x32_bf16 v[112:115], v[174:177], v[208:211], v[112:115]
	v_mfma_f32_16x16x32_bf16 v[100:103], v[166:169], v[216:219], v[100:103]
	v_mfma_f32_16x16x32_bf16 v[96:99], v[174:177], v[216:219], v[96:99]
	v_mfma_f32_16x16x32_bf16 v[84:87], v[166:169], v[224:227], v[84:87]
	v_mfma_f32_16x16x32_bf16 v[80:83], v[174:177], v[224:227], v[80:83]
	v_mfma_f32_16x16x32_bf16 v[68:71], v[166:169], v[232:235], v[68:71]
	v_mfma_f32_16x16x32_bf16 v[64:67], v[174:177], v[232:235], v[64:67]
	s_setprio 0
	s_barrier
	s_add_i32 s19, s19, s34
	v_lshl_add_u64 v[182:183], s[68:69], 0, v[130:131]
	s_mov_b32 m0, s19
	ds_read_b128 v[178:181], v153 offset:16384
	ds_read_b128 v[208:211], v153 offset:17408
	ds_read_b128 v[212:215], v153 offset:18432
	ds_read_b128 v[216:219], v153 offset:19456
	ds_read_b128 v[220:223], v153 offset:20480
	ds_read_b128 v[224:227], v153 offset:21504
	ds_read_b128 v[228:231], v153 offset:22528
	ds_read_b128 v[232:235], v153 offset:23552
	global_load_lds_dwordx4 v[182:183], off
	s_add_i32 m0, s19, 0x2000
	s_add_u32 s68, s68, s10
	v_lshl_add_u64 v[236:237], v[182:183], 0, s[8:9]
	s_addc_u32 s69, s69, s11
	s_add_i32 s4, s4, s34
	global_load_lds_dwordx4 v[236:237], off
	v_lshl_add_u64 v[238:239], s[68:69], 0, v[130:131]
	s_mov_b32 m0, s4
	v_lshl_add_u64 v[240:241], v[238:239], 0, s[8:9]
	global_load_lds_dwordx4 v[238:239], off
	s_add_i32 m0, s4, 0x2000
	v_lshl_add_u64 v[242:243], s[14:15], 0, v[136:137]
	global_load_lds_dwordx4 v[240:241], off
	s_mov_b32 m0, s35
	v_lshl_add_u64 v[244:245], v[242:243], 0, s[8:9]
	global_load_lds_dwordx4 v[242:243], off
	s_mov_b32 m0, s36
	s_nop 0
	global_load_lds_dwordx4 v[244:245], off
	s_waitcnt vmcnt(8)
	s_waitcnt lgkmcnt(0)
	s_barrier
; #define PG8_STAGE(bufoff, gbase, voff) do { _Pragma("unroll") for (int _i = 0; _i < 2; ++_i) \
;         __builtin_amdgcn_global_load_lds((const unsigned*)((const char*)(gbase) + _i * rdelta + (voff)), (LAS unsigned*)(lds + (bufoff) + ldsw + _i * 8192), 16, 0, 0); } while (0)
; #define PG8_LDA(dst, b, h) do { _Pragma("unroll") for (int m = 0; m < 4; ++m) _Pragma("unroll") for (int k = 0; k < 2; ++k) dst[m][k] = *(const LAS bf16x8*)(lds + PG8_SA(b, h) + aoff + m * 2048 + k * 1024); } while (0)
; #define PG8_LDB(dst, b, h) do { _Pragma("unroll") for (int n = 0; n < 2; ++n) _Pragma("unroll") for (int k = 0; k < 2; ++k) dst[n][k] = *(const LAS bf16x8*)(lds + PG8_SB(b, h) + boff + n * 2048 + k * 1024); } while (0)
; #define PG8_MMA(ai, bj, At, Bt) do { __builtin_amdgcn_s_setprio(1); _Pragma("unroll") for (int m = 0; m < 4; ++m) _Pragma("unroll") for (int n = 0; n < 2; ++n) _Pragma("unroll") for (int k = 0; k < 2; ++k) \
;         acc[ai][bj][m][n] = __builtin_amdgcn_mfma_f32_16x16x32_bf16(Bt[n][k], At[m][k], acc[ai][bj][m][n], 0, 0, 0); __builtin_amdgcn_s_setprio(0); } while (0)
; #define PG8_WAIT_V(n) asm volatile("s_waitcnt vmcnt(" #n ")" ::: "memory")
; #define PG8_WAIT_L(n) asm volatile("s_waitcnt lgkmcnt(" #n ")" ::: "memory")
; #define PG8_BAR __builtin_amdgcn_s_barrier()
; #define PG8_SCHED __builtin_amdgcn_sched_barrier(0)
; template <class Epi, class Sched, bool ALIGN_EPI, bool SP2>
; __device__ __forceinline__ void gemm_phase(LAS unsigned char* lds, const Gemm g, const Sched& S, const Epi& E) {
;     ...
;             PG8_WAIT_V(8); PG8_WAIT_L(0); PG8_BAR; PG8_MMA(1, 0, At, B0); PG8_MMA(1, 1, At, B1); PG8_BAR; PG8_SCHED;
;             PG8_LDB(B0, 1, 0); PG8_LDB(B1, 1, 1); PG8_SCHED; PG8_LDA(At, 1, 0); PG8_STAGE(PG8_SA(0, 1), a2 + hstep, voffA);
;             PG8_WAIT_V(8); PG8_WAIT_L(0); PG8_BAR; PG8_MMA(0, 0, At, B0); PG8_MMA(0, 1, At, B1); PG8_BAR; PG8_SCHED;
	s_setprio 1
	s_waitcnt lgkmcnt(0)
	v_mfma_f32_16x16x32_bf16 v[60:63], v[142:145], v[178:181], v[60:63]
	v_mfma_f32_16x16x32_bf16 v[56:59], v[154:157], v[178:181], v[56:59]
	v_mfma_f32_16x16x32_bf16 v[44:47], v[142:145], v[212:215], v[44:47]
	v_mfma_f32_16x16x32_bf16 v[40:43], v[154:157], v[212:215], v[40:43]
	v_mfma_f32_16x16x32_bf16 v[28:31], v[142:145], v[220:223], v[28:31]
	v_mfma_f32_16x16x32_bf16 v[24:27], v[154:157], v[220:223], v[24:27]
	v_mfma_f32_16x16x32_bf16 v[12:15], v[142:145], v[228:231], v[12:15]
	v_mfma_f32_16x16x32_bf16 v[8:11], v[154:157], v[228:231], v[8:11]
	v_mfma_f32_16x16x32_bf16 v[60:63], v[146:149], v[208:211], v[60:63]
	v_mfma_f32_16x16x32_bf16 v[56:59], v[158:161], v[208:211], v[56:59]
	v_mfma_f32_16x16x32_bf16 v[44:47], v[146:149], v[216:219], v[44:47]
	v_mfma_f32_16x16x32_bf16 v[40:43], v[158:161], v[216:219], v[40:43]
	v_mfma_f32_16x16x32_bf16 v[28:31], v[146:149], v[224:227], v[28:31]
	v_mfma_f32_16x16x32_bf16 v[24:27], v[158:161], v[224:227], v[24:27]
	v_mfma_f32_16x16x32_bf16 v[12:15], v[146:149], v[232:235], v[12:15]
	v_mfma_f32_16x16x32_bf16 v[8:11], v[158:161], v[232:235], v[8:11]
	s_setprio 0
	s_setprio 1
	v_mfma_f32_16x16x32_bf16 v[52:55], v[162:165], v[178:181], v[52:55]
	v_mfma_f32_16x16x32_bf16 v[48:51], v[170:173], v[178:181], v[48:51]
	v_mfma_f32_16x16x32_bf16 v[36:39], v[162:165], v[212:215], v[36:39]
	v_mfma_f32_16x16x32_bf16 v[32:35], v[170:173], v[212:215], v[32:35]
	v_mfma_f32_16x16x32_bf16 v[20:23], v[162:165], v[220:223], v[20:23]
	v_mfma_f32_16x16x32_bf16 v[16:19], v[170:173], v[220:223], v[16:19]
	v_mfma_f32_16x16x32_bf16 v[4:7], v[162:165], v[228:231], v[4:7]
	v_mfma_f32_16x16x32_bf16 v[0:3], v[170:173], v[228:231], v[0:3]
	v_mfma_f32_16x16x32_bf16 v[52:55], v[166:169], v[208:211], v[52:55]
	v_mfma_f32_16x16x32_bf16 v[48:51], v[174:177], v[208:211], v[48:51]
	v_mfma_f32_16x16x32_bf16 v[36:39], v[166:169], v[216:219], v[36:39]
	v_mfma_f32_16x16x32_bf16 v[32:35], v[174:177], v[216:219], v[32:35]
	v_mfma_f32_16x16x32_bf16 v[20:23], v[166:169], v[224:227], v[20:23]
	v_mfma_f32_16x16x32_bf16 v[16:19], v[174:177], v[224:227], v[16:19]
	v_mfma_f32_16x16x32_bf16 v[4:7], v[166:169], v[232:235], v[4:7]
	v_mfma_f32_16x16x32_bf16 v[0:3], v[174:177], v[232:235], v[0:3]
	s_setprio 0
	s_barrier
	s_add_i32 s4, 0, 0x18000
	v_add_u32_e32 v128, s4, v151
	s_add_i32 s19, 0, 0x1c000
	ds_read_b128 v[142:145], v128
	ds_read_b128 v[146:149], v128 offset:1024
	ds_read_b128 v[154:157], v128 offset:2048
	ds_read_b128 v[158:161], v128 offset:3072
	v_add_u32_e32 v128, s19, v151
	ds_read_b128 v[162:165], v128
	ds_read_b128 v[166:169], v128 offset:1024
	ds_read_b128 v[170:173], v128 offset:2048
	ds_read_b128 v[174:177], v128 offset:3072
	s_add_u32 s14, s14, s10
	s_addc_u32 s15, s15, s11
	s_mov_b32 m0, s37
	v_lshl_add_u64 v[246:247], s[14:15], 0, v[136:137]
	ds_read_b128 v[178:181], v153 offset:32768
	ds_read_b128 v[208:211], v153 offset:33792
	ds_read_b128 v[212:215], v153 offset:34816
	ds_read_b128 v[216:219], v153 offset:35840
	ds_read_b128 v[220:223], v153 offset:36864
	ds_read_b128 v[224:227], v153 offset:37888
	ds_read_b128 v[228:231], v153 offset:38912
	ds_read_b128 v[232:235], v153 offset:39936
	global_load_lds_dwordx4 v[246:247], off
	v_lshl_add_u64 v[246:247], v[246:247], 0, s[8:9]
	s_mov_b32 m0, s38
	s_nop 0
	global_load_lds_dwordx4 v[246:247], off
	s_waitcnt vmcnt(8)
	s_waitcnt lgkmcnt(0)
	s_barrier
	s_setprio 1
	s_waitcnt lgkmcnt(0)
	v_mfma_f32_16x16x32_bf16 v[120:123], v[142:145], v[178:181], v[120:123]
	v_mfma_f32_16x16x32_bf16 v[124:127], v[154:157], v[178:181], v[124:127]
	v_mfma_f32_16x16x32_bf16 v[108:111], v[142:145], v[212:215], v[108:111]
	v_mfma_f32_16x16x32_bf16 v[104:107], v[154:157], v[212:215], v[104:107]
	v_mfma_f32_16x16x32_bf16 v[92:95], v[142:145], v[220:223], v[92:95]
	v_mfma_f32_16x16x32_bf16 v[88:91], v[154:157], v[220:223], v[88:91]
	v_mfma_f32_16x16x32_bf16 v[76:79], v[142:145], v[228:231], v[76:79]
	v_mfma_f32_16x16x32_bf16 v[72:75], v[154:157], v[228:231], v[72:75]
	v_mfma_f32_16x16x32_bf16 v[120:123], v[146:149], v[208:211], v[120:123]
	v_mfma_f32_16x16x32_bf16 v[124:127], v[158:161], v[208:211], v[124:127]
	v_mfma_f32_16x16x32_bf16 v[108:111], v[146:149], v[216:219], v[108:111]
	v_mfma_f32_16x16x32_bf16 v[104:107], v[158:161], v[216:219], v[104:107]
	v_mfma_f32_16x16x32_bf16 v[92:95], v[146:149], v[224:227], v[92:95]
	v_mfma_f32_16x16x32_bf16 v[88:91], v[158:161], v[224:227], v[88:91]
	v_mfma_f32_16x16x32_bf16 v[76:79], v[146:149], v[232:235], v[76:79]
	v_mfma_f32_16x16x32_bf16 v[72:75], v[158:161], v[232:235], v[72:75]
	s_setprio 0
	s_setprio 1
	v_mfma_f32_16x16x32_bf16 v[116:119], v[162:165], v[178:181], v[116:119]
	v_mfma_f32_16x16x32_bf16 v[112:115], v[170:173], v[178:181], v[112:115]
	v_mfma_f32_16x16x32_bf16 v[100:103], v[162:165], v[212:215], v[100:103]
	v_mfma_f32_16x16x32_bf16 v[96:99], v[170:173], v[212:215], v[96:99]
	v_mfma_f32_16x16x32_bf16 v[84:87], v[162:165], v[220:223], v[84:87]
	v_mfma_f32_16x16x32_bf16 v[80:83], v[170:173], v[220:223], v[80:83]
	v_mfma_f32_16x16x32_bf16 v[68:71], v[162:165], v[228:231], v[68:71]
	v_mfma_f32_16x16x32_bf16 v[64:67], v[170:173], v[228:231], v[64:67]
	v_mfma_f32_16x16x32_bf16 v[116:119], v[166:169], v[208:211], v[116:119]
	v_mfma_f32_16x16x32_bf16 v[112:115], v[174:177], v[208:211], v[112:115]
	v_mfma_f32_16x16x32_bf16 v[100:103], v[166:169], v[216:219], v[100:103]
	v_mfma_f32_16x16x32_bf16 v[96:99], v[174:177], v[216:219], v[96:99]
	v_mfma_f32_16x16x32_bf16 v[84:87], v[166:169], v[224:227], v[84:87]
	v_mfma_f32_16x16x32_bf16 v[80:83], v[174:177], v[224:227], v[80:83]
	v_mfma_f32_16x16x32_bf16 v[68:71], v[166:169], v[232:235], v[68:71]
	v_mfma_f32_16x16x32_bf16 v[64:67], v[174:177], v[232:235], v[64:67]
	s_setprio 0
	s_barrier
; #define PG8_STAGE(bufoff, gbase, voff) do { _Pragma("unroll") for (int _i = 0; _i < 2; ++_i) \
;         __builtin_amdgcn_global_load_lds((const unsigned*)((const char*)(gbase) + _i * rdelta + (voff)), (LAS unsigned*)(lds + (bufoff) + ldsw + _i * 8192), 16, 0, 0); } while (0)
; #define PG8_LDA(dst, b, h) do { _Pragma("unroll") for (int m = 0; m < 4; ++m) _Pragma("unroll") for (int k = 0; k < 2; ++k) dst[m][k] = *(const LAS bf16x8*)(lds + PG8_SA(b, h) + aoff + m * 2048 + k * 1024); } while (0)
; #define PG8_MMA(ai, bj, At, Bt) do { __builtin_amdgcn_s_setprio(1); _Pragma("unroll") for (int m = 0; m < 4; ++m) _Pragma("unroll") for (int n = 0; n < 2; ++n) _Pragma("unroll") for (int k = 0; k < 2; ++k) \
;         acc[ai][bj][m][n] = __builtin_amdgcn_mfma_f32_16x16x32_bf16(Bt[n][k], At[m][k], acc[ai][bj][m][n], 0, 0, 0); __builtin_amdgcn_s_setprio(0); } while (0)
; #define PG8_WAIT_V(n) asm volatile("s_waitcnt vmcnt(" #n ")" ::: "memory")
; #define PG8_WAIT_L(n) asm volatile("s_waitcnt lgkmcnt(" #n ")" ::: "memory")
; #define PG8_BAR __builtin_amdgcn_s_barrier()
; #define PG8_SCHED __builtin_amdgcn_sched_barrier(0)
; template <class Epi, class Sched, bool ALIGN_EPI, bool SP2>
; __device__ __forceinline__ void gemm_phase(LAS unsigned char* lds, const Gemm g, const Sched& S, const Epi& E) {
;     ...
;             PG8_LDA(At, 1, 1); PG8_STAGE(PG8_SB(1, 0), b3, voffB); PG8_STAGE(PG8_SB(1, 1), b3 + hstep, voffB); PG8_STAGE(PG8_SA(1, 0), a3, voffA);
;             PG8_WAIT_V(8); PG8_WAIT_L(0); PG8_BAR; PG8_MMA(1, 0, At, B0); PG8_MMA(1, 1, At, B1); PG8_BAR; PG8_SCHED;
;         }
	s_add_i32 s4, s4, s34
	v_lshl_add_u64 v[182:183], v[182:183], 0, s[30:31]
	s_mov_b32 m0, s4
	ds_read_b128 v[178:181], v153 offset:49152
	ds_read_b128 v[208:211], v153 offset:50176
	ds_read_b128 v[212:215], v153 offset:51200
	ds_read_b128 v[216:219], v153 offset:52224
	ds_read_b128 v[220:223], v153 offset:53248
	ds_read_b128 v[224:227], v153 offset:54272
	ds_read_b128 v[228:231], v153 offset:55296
	ds_read_b128 v[232:235], v153 offset:56320
	global_load_lds_dwordx4 v[182:183], off
	v_lshl_add_u64 v[182:183], v[236:237], 0, s[30:31]
	s_add_i32 m0, s4, 0x2000
	s_add_i32 s4, s19, s34
	global_load_lds_dwordx4 v[182:183], off
	v_lshl_add_u64 v[182:183], v[238:239], 0, s[30:31]
	s_mov_b32 m0, s4
	s_nop 0
	global_load_lds_dwordx4 v[182:183], off
	v_lshl_add_u64 v[182:183], v[240:241], 0, s[30:31]
	s_add_i32 m0, s4, 0x2000
	s_nop 0
	global_load_lds_dwordx4 v[182:183], off
	v_lshl_add_u64 v[182:183], v[242:243], 0, s[30:31]
	s_mov_b32 m0, s40
	s_nop 0
	global_load_lds_dwordx4 v[182:183], off
	v_lshl_add_u64 v[182:183], v[244:245], 0, s[30:31]
	s_mov_b32 m0, s41
	s_nop 0
	global_load_lds_dwordx4 v[182:183], off
	s_waitcnt vmcnt(8)
	s_waitcnt lgkmcnt(0)
	s_barrier
	s_setprio 1
	s_waitcnt lgkmcnt(0)
	v_mfma_f32_16x16x32_bf16 v[60:63], v[142:145], v[178:181], v[60:63]
	v_mfma_f32_16x16x32_bf16 v[56:59], v[154:157], v[178:181], v[56:59]
	v_mfma_f32_16x16x32_bf16 v[44:47], v[142:145], v[212:215], v[44:47]
	v_mfma_f32_16x16x32_bf16 v[40:43], v[154:157], v[212:215], v[40:43]
	v_mfma_f32_16x16x32_bf16 v[28:31], v[142:145], v[220:223], v[28:31]
	v_mfma_f32_16x16x32_bf16 v[24:27], v[154:157], v[220:223], v[24:27]
	v_mfma_f32_16x16x32_bf16 v[12:15], v[142:145], v[228:231], v[12:15]
	v_mfma_f32_16x16x32_bf16 v[8:11], v[154:157], v[228:231], v[8:11]
	v_mfma_f32_16x16x32_bf16 v[60:63], v[146:149], v[208:211], v[60:63]
	v_mfma_f32_16x16x32_bf16 v[56:59], v[158:161], v[208:211], v[56:59]
	v_mfma_f32_16x16x32_bf16 v[44:47], v[146:149], v[216:219], v[44:47]
	v_mfma_f32_16x16x32_bf16 v[40:43], v[158:161], v[216:219], v[40:43]
	v_mfma_f32_16x16x32_bf16 v[28:31], v[146:149], v[224:227], v[28:31]
	v_mfma_f32_16x16x32_bf16 v[24:27], v[158:161], v[224:227], v[24:27]
	v_mfma_f32_16x16x32_bf16 v[12:15], v[146:149], v[232:235], v[12:15]
	v_mfma_f32_16x16x32_bf16 v[8:11], v[158:161], v[232:235], v[8:11]
	s_setprio 0
	s_setprio 1
	v_mfma_f32_16x16x32_bf16 v[52:55], v[162:165], v[178:181], v[52:55]
	v_mfma_f32_16x16x32_bf16 v[48:51], v[170:173], v[178:181], v[48:51]
	v_mfma_f32_16x16x32_bf16 v[36:39], v[162:165], v[212:215], v[36:39]
	v_mfma_f32_16x16x32_bf16 v[32:35], v[170:173], v[212:215], v[32:35]
	v_mfma_f32_16x16x32_bf16 v[20:23], v[162:165], v[220:223], v[20:23]
	v_mfma_f32_16x16x32_bf16 v[16:19], v[170:173], v[220:223], v[16:19]
	v_mfma_f32_16x16x32_bf16 v[4:7], v[162:165], v[228:231], v[4:7]
	v_mfma_f32_16x16x32_bf16 v[0:3], v[170:173], v[228:231], v[0:3]
	v_mfma_f32_16x16x32_bf16 v[52:55], v[166:169], v[208:211], v[52:55]
	v_mfma_f32_16x16x32_bf16 v[48:51], v[174:177], v[208:211], v[48:51]
	v_mfma_f32_16x16x32_bf16 v[36:39], v[166:169], v[216:219], v[36:39]
	v_mfma_f32_16x16x32_bf16 v[32:35], v[174:177], v[216:219], v[32:35]
	v_mfma_f32_16x16x32_bf16 v[20:23], v[166:169], v[224:227], v[20:23]
	v_mfma_f32_16x16x32_bf16 v[16:19], v[174:177], v[224:227], v[16:19]
	v_mfma_f32_16x16x32_bf16 v[4:7], v[166:169], v[232:235], v[4:7]
	v_mfma_f32_16x16x32_bf16 v[0:3], v[174:177], v[232:235], v[0:3]
	s_setprio 0
	s_add_u32 s6, s6, 0x100
	s_addc_u32 s7, s7, 0
	s_add_u32 s16, s16, 0x100
	s_addc_u32 s17, s17, 0
	s_cmp_ge_i32 s18, s62
	s_mov_b32 s4, s18
	s_barrier
	s_cbranch_scc0 .LBB0_805

; #define PG8_STAGE(bufoff, gbase, voff) do { _Pragma("unroll") for (int _i = 0; _i < 2; ++_i) \
;         __builtin_amdgcn_global_load_lds((const unsigned*)((const char*)(gbase) + _i * rdelta + (voff)), (LAS unsigned*)(lds + (bufoff) + ldsw + _i * 8192), 16, 0, 0); } while (0)
; #define PG8_LDA(dst, b, h) do { _Pragma("unroll") for (int m = 0; m < 4; ++m) _Pragma("unroll") for (int k = 0; k < 2; ++k) dst[m][k] = *(const LAS bf16x8*)(lds + PG8_SA(b, h) + aoff + m * 2048 + k * 1024); } while (0)
; #define PG8_LDB(dst, b, h) do { _Pragma("unroll") for (int n = 0; n < 2; ++n) _Pragma("unroll") for (int k = 0; k < 2; ++k) dst[n][k] = *(const LAS bf16x8*)(lds + PG8_SB(b, h) + boff + n * 2048 + k * 1024); } while (0)
; #define PG8_MMA(ai, bj, At, Bt) do { __builtin_amdgcn_s_setprio(1); _Pragma("unroll") for (int m = 0; m < 4; ++m) _Pragma("unroll") for (int n = 0; n < 2; ++n) _Pragma("unroll") for (int k = 0; k < 2; ++k) \
;         acc[ai][bj][m][n] = __builtin_amdgcn_mfma_f32_16x16x32_bf16(Bt[n][k], At[m][k], acc[ai][bj][m][n], 0, 0, 0); __builtin_amdgcn_s_setprio(0); } while (0)
; #define PG8_WAIT_V(n) asm volatile("s_waitcnt vmcnt(" #n ")" ::: "memory")
; #define PG8_WAIT_L(n) asm volatile("s_waitcnt lgkmcnt(" #n ")" ::: "memory")
; template <class Epi, class Sched, bool ALIGN_EPI, bool SP2>
; __device__ __forceinline__ void gemm_phase(LAS unsigned char* lds, const Gemm g, const Sched& S, const Epi& E) {
;     ...
;         for (int t = 0; t < nt; t += 2) {
;             if constexpr (Epi::HOOK) { if (t == Epi::T1 || t == Epi::T2) E.hook(acc, ui, t, wr, fr); }
;             const bool last = (t == nt - 2);
;             const char* a1 = cA + (size_t)(t + 1) * kstep;
;             const char* a2 = last ? nA : cA + (size_t)(t + 2) * kstep; const char* b2 = last ? nB : cB + (size_t)(t + 2) * kstep;
;             const char* a3 = a2 + kstep; const char* b3 = b2 + kstep;
;             PG8_LDB(B0, 0, 0); PG8_LDB(B1, 0, 1); PG8_SCHED; PG8_LDA(At, 0, 0); PG8_STAGE(PG8_SA(1, 1), a1 + hstep, voffA);
;             PG8_WAIT_V(8); PG8_WAIT_L(0); PG8_BAR; PG8_MMA(0, 0, At, B0); PG8_MMA(0, 1, At, B1); PG8_BAR; PG8_SCHED;
;             PG8_LDA(At, 0, 1); PG8_STAGE(PG8_SB(0, 0), b2, voffB); PG8_STAGE(PG8_SB(0, 1), b2 + hstep, voffB); PG8_STAGE(PG8_SA(0, 0), a2, voffA);
;             PG8_WAIT_V(8); PG8_WAIT_L(0); PG8_BAR; PG8_MMA(1, 0, At, B0); PG8_MMA(1, 1, At, B1); PG8_BAR; PG8_SCHED;
.LBB0_862:
	s_add_i32 s63, s4, 2
	s_add_u32 s16, s14, 0x80
	s_addc_u32 s17, s15, 0
	s_add_i32 s66, 0, 0x10000
	s_cmp_eq_u32 s57, s4
	s_cselect_b32 s17, s7, s17
	s_cselect_b32 s16, s6, s16
	v_add_u32_e32 v128, s66, v145
	s_cselect_b32 s65, s55, s19
	s_cselect_b32 s64, s54, s18
	s_add_i32 s4, 0, 0x14000
	ds_read_b128 v[148:151], v128
	ds_read_b128 v[152:155], v128 offset:1024
	ds_read_b128 v[156:159], v128 offset:2048
	ds_read_b128 v[160:163], v128 offset:3072
	v_add_u32_e32 v128, s4, v145
	ds_read_b128 v[164:167], v128
	ds_read_b128 v[168:171], v128 offset:1024
	ds_read_b128 v[172:175], v128 offset:2048
	ds_read_b128 v[176:179], v128 offset:3072
	v_lshl_add_u64 v[142:143], s[14:15], 0, v[138:139]
	s_add_i32 m0, s35, 0xc000
	ds_read_b128 v[180:183], v147
	ds_read_b128 v[208:211], v147 offset:1024
	ds_read_b128 v[212:215], v147 offset:2048
	ds_read_b128 v[216:219], v147 offset:3072
	ds_read_b128 v[220:223], v147 offset:4096
	ds_read_b128 v[224:227], v147 offset:5120
	ds_read_b128 v[228:231], v147 offset:6144
	ds_read_b128 v[232:235], v147 offset:7168
	global_load_lds_dwordx4 v[142:143], off
	v_lshl_add_u64 v[142:143], s[14:15], 0, v[140:141]
	s_add_i32 m0, s35, 0xe000
	s_nop 0
	global_load_lds_dwordx4 v[142:143], off
	s_waitcnt vmcnt(8)
	s_waitcnt lgkmcnt(0)
	s_barrier
	s_setprio 1
	s_waitcnt lgkmcnt(0)
	v_mfma_f32_16x16x32_bf16 v[120:123], v[148:151], v[180:183], v[120:123]
	v_mfma_f32_16x16x32_bf16 v[124:127], v[156:159], v[180:183], v[124:127]
	v_mfma_f32_16x16x32_bf16 v[108:111], v[148:151], v[212:215], v[108:111]
	v_mfma_f32_16x16x32_bf16 v[104:107], v[156:159], v[212:215], v[104:107]
	v_mfma_f32_16x16x32_bf16 v[92:95], v[148:151], v[220:223], v[92:95]
	v_mfma_f32_16x16x32_bf16 v[88:91], v[156:159], v[220:223], v[88:91]
	v_mfma_f32_16x16x32_bf16 v[76:79], v[148:151], v[228:231], v[76:79]
	v_mfma_f32_16x16x32_bf16 v[72:75], v[156:159], v[228:231], v[72:75]
	v_mfma_f32_16x16x32_bf16 v[120:123], v[152:155], v[208:211], v[120:123]
	v_mfma_f32_16x16x32_bf16 v[124:127], v[160:163], v[208:211], v[124:127]
	v_mfma_f32_16x16x32_bf16 v[108:111], v[152:155], v[216:219], v[108:111]
	v_mfma_f32_16x16x32_bf16 v[104:107], v[160:163], v[216:219], v[104:107]
	v_mfma_f32_16x16x32_bf16 v[92:95], v[152:155], v[224:227], v[92:95]
	v_mfma_f32_16x16x32_bf16 v[88:91], v[160:163], v[224:227], v[88:91]
	v_mfma_f32_16x16x32_bf16 v[76:79], v[152:155], v[232:235], v[76:79]
	v_mfma_f32_16x16x32_bf16 v[72:75], v[160:163], v[232:235], v[72:75]
	s_setprio 0
	s_setprio 1
	v_mfma_f32_16x16x32_bf16 v[116:119], v[164:167], v[180:183], v[116:119]
	v_mfma_f32_16x16x32_bf16 v[112:115], v[172:175], v[180:183], v[112:115]
	v_mfma_f32_16x16x32_bf16 v[100:103], v[164:167], v[212:215], v[100:103]
	v_mfma_f32_16x16x32_bf16 v[96:99], v[172:175], v[212:215], v[96:99]
	v_mfma_f32_16x16x32_bf16 v[84:87], v[164:167], v[220:223], v[84:87]
	v_mfma_f32_16x16x32_bf16 v[80:83], v[172:175], v[220:223], v[80:83]
	v_mfma_f32_16x16x32_bf16 v[68:71], v[164:167], v[228:231], v[68:71]
	v_mfma_f32_16x16x32_bf16 v[64:67], v[172:175], v[228:231], v[64:67]
	v_mfma_f32_16x16x32_bf16 v[116:119], v[168:171], v[208:211], v[116:119]
	v_mfma_f32_16x16x32_bf16 v[112:115], v[176:179], v[208:211], v[112:115]
	v_mfma_f32_16x16x32_bf16 v[100:103], v[168:171], v[216:219], v[100:103]
	v_mfma_f32_16x16x32_bf16 v[96:99], v[176:179], v[216:219], v[96:99]
	v_mfma_f32_16x16x32_bf16 v[84:87], v[168:171], v[224:227], v[84:87]
	v_mfma_f32_16x16x32_bf16 v[80:83], v[176:179], v[224:227], v[80:83]
	v_mfma_f32_16x16x32_bf16 v[68:71], v[168:171], v[232:235], v[68:71]
	v_mfma_f32_16x16x32_bf16 v[64:67], v[176:179], v[232:235], v[64:67]
	s_setprio 0
	s_barrier
	s_add_i32 s66, s66, s34
	v_lshl_add_u64 v[142:143], s[64:65], 0, v[130:131]
	s_mov_b32 m0, s66
	ds_read_b128 v[180:183], v147 offset:16384
	ds_read_b128 v[208:211], v147 offset:17408
	ds_read_b128 v[212:215], v147 offset:18432
	ds_read_b128 v[216:219], v147 offset:19456
	ds_read_b128 v[220:223], v147 offset:20480
	ds_read_b128 v[224:227], v147 offset:21504
	ds_read_b128 v[228:231], v147 offset:22528
	ds_read_b128 v[232:235], v147 offset:23552
	global_load_lds_dwordx4 v[142:143], off
	s_add_i32 m0, s66, 0x2000
	s_add_u32 s64, s64, s10
	v_lshl_add_u64 v[236:237], v[142:143], 0, s[8:9]
	s_addc_u32 s65, s65, s11
	s_add_i32 s4, s4, s34
	global_load_lds_dwordx4 v[236:237], off
	v_lshl_add_u64 v[238:239], s[64:65], 0, v[130:131]
	s_mov_b32 m0, s4
	v_lshl_add_u64 v[240:241], v[238:239], 0, s[8:9]
	global_load_lds_dwordx4 v[238:239], off
	s_add_i32 m0, s4, 0x2000
	v_lshl_add_u64 v[242:243], s[16:17], 0, v[136:137]
	global_load_lds_dwordx4 v[240:241], off
	s_mov_b32 m0, s35
	v_lshl_add_u64 v[244:245], v[242:243], 0, s[8:9]
	global_load_lds_dwordx4 v[242:243], off
	s_mov_b32 m0, s36
	s_nop 0
	global_load_lds_dwordx4 v[244:245], off
	s_waitcnt vmcnt(8)
	s_waitcnt lgkmcnt(0)
	s_barrier
; #define PG8_STAGE(bufoff, gbase, voff) do { _Pragma("unroll") for (int _i = 0; _i < 2; ++_i) \
;         __builtin_amdgcn_global_load_lds((const unsigned*)((const char*)(gbase) + _i * rdelta + (voff)), (LAS unsigned*)(lds + (bufoff) + ldsw + _i * 8192), 16, 0, 0); } while (0)
; #define PG8_LDA(dst, b, h) do { _Pragma("unroll") for (int m = 0; m < 4; ++m) _Pragma("unroll") for (int k = 0; k < 2; ++k) dst[m][k] = *(const LAS bf16x8*)(lds + PG8_SA(b, h) + aoff + m * 2048 + k * 1024); } while (0)
; #define PG8_LDB(dst, b, h) do { _Pragma("unroll") for (int n = 0; n < 2; ++n) _Pragma("unroll") for (int k = 0; k < 2; ++k) dst[n][k] = *(const LAS bf16x8*)(lds + PG8_SB(b, h) + boff + n * 2048 + k * 1024); } while (0)
; #define PG8_MMA(ai, bj, At, Bt) do { __builtin_amdgcn_s_setprio(1); _Pragma("unroll") for (int m = 0; m < 4; ++m) _Pragma("unroll") for (int n = 0; n < 2; ++n) _Pragma("unroll") for (int k = 0; k < 2; ++k) \
;         acc[ai][bj][m][n] = __builtin_amdgcn_mfma_f32_16x16x32_bf16(Bt[n][k], At[m][k], acc[ai][bj][m][n], 0, 0, 0); __builtin_amdgcn_s_setprio(0); } while (0)
; #define PG8_WAIT_V(n) asm volatile("s_waitcnt vmcnt(" #n ")" ::: "memory")
; #define PG8_WAIT_L(n) asm volatile("s_waitcnt lgkmcnt(" #n ")" ::: "memory")
; #define PG8_BAR __builtin_amdgcn_s_barrier()
; #define PG8_SCHED __builtin_amdgcn_sched_barrier(0)
; template <class Epi, class Sched, bool ALIGN_EPI, bool SP2>
; __device__ __forceinline__ void gemm_phase(LAS unsigned char* lds, const Gemm g, const Sched& S, const Epi& E) {
;     ...
;             PG8_WAIT_V(8); PG8_WAIT_L(0); PG8_BAR; PG8_MMA(1, 0, At, B0); PG8_MMA(1, 1, At, B1); PG8_BAR; PG8_SCHED;
;             PG8_LDB(B0, 1, 0); PG8_LDB(B1, 1, 1); PG8_SCHED; PG8_LDA(At, 1, 0); PG8_STAGE(PG8_SA(0, 1), a2 + hstep, voffA);
;             PG8_WAIT_V(8); PG8_WAIT_L(0); PG8_BAR; PG8_MMA(0, 0, At, B0); PG8_MMA(0, 1, At, B1); PG8_BAR; PG8_SCHED;
	s_setprio 1
	s_waitcnt lgkmcnt(0)
	v_mfma_f32_16x16x32_bf16 v[60:63], v[148:151], v[180:183], v[60:63]
	v_mfma_f32_16x16x32_bf16 v[56:59], v[156:159], v[180:183], v[56:59]
	v_mfma_f32_16x16x32_bf16 v[44:47], v[148:151], v[212:215], v[44:47]
	v_mfma_f32_16x16x32_bf16 v[40:43], v[156:159], v[212:215], v[40:43]
	v_mfma_f32_16x16x32_bf16 v[28:31], v[148:151], v[220:223], v[28:31]
	v_mfma_f32_16x16x32_bf16 v[24:27], v[156:159], v[220:223], v[24:27]
	v_mfma_f32_16x16x32_bf16 v[12:15], v[148:151], v[228:231], v[12:15]
	v_mfma_f32_16x16x32_bf16 v[8:11], v[156:159], v[228:231], v[8:11]
	v_mfma_f32_16x16x32_bf16 v[60:63], v[152:155], v[208:211], v[60:63]
	v_mfma_f32_16x16x32_bf16 v[56:59], v[160:163], v[208:211], v[56:59]
	v_mfma_f32_16x16x32_bf16 v[44:47], v[152:155], v[216:219], v[44:47]
	v_mfma_f32_16x16x32_bf16 v[40:43], v[160:163], v[216:219], v[40:43]
	v_mfma_f32_16x16x32_bf16 v[28:31], v[152:155], v[224:227], v[28:31]
	v_mfma_f32_16x16x32_bf16 v[24:27], v[160:163], v[224:227], v[24:27]
	v_mfma_f32_16x16x32_bf16 v[12:15], v[152:155], v[232:235], v[12:15]
	v_mfma_f32_16x16x32_bf16 v[8:11], v[160:163], v[232:235], v[8:11]
	s_setprio 0
	s_setprio 1
	v_mfma_f32_16x16x32_bf16 v[52:55], v[164:167], v[180:183], v[52:55]
	v_mfma_f32_16x16x32_bf16 v[48:51], v[172:175], v[180:183], v[48:51]
	v_mfma_f32_16x16x32_bf16 v[36:39], v[164:167], v[212:215], v[36:39]
	v_mfma_f32_16x16x32_bf16 v[32:35], v[172:175], v[212:215], v[32:35]
	v_mfma_f32_16x16x32_bf16 v[20:23], v[164:167], v[220:223], v[20:23]
	v_mfma_f32_16x16x32_bf16 v[16:19], v[172:175], v[220:223], v[16:19]
	v_mfma_f32_16x16x32_bf16 v[4:7], v[164:167], v[228:231], v[4:7]
	v_mfma_f32_16x16x32_bf16 v[0:3], v[172:175], v[228:231], v[0:3]
	v_mfma_f32_16x16x32_bf16 v[52:55], v[168:171], v[208:211], v[52:55]
	v_mfma_f32_16x16x32_bf16 v[48:51], v[176:179], v[208:211], v[48:51]
	v_mfma_f32_16x16x32_bf16 v[36:39], v[168:171], v[216:219], v[36:39]
	v_mfma_f32_16x16x32_bf16 v[32:35], v[176:179], v[216:219], v[32:35]
	v_mfma_f32_16x16x32_bf16 v[20:23], v[168:171], v[224:227], v[20:23]
	v_mfma_f32_16x16x32_bf16 v[16:19], v[176:179], v[224:227], v[16:19]
	v_mfma_f32_16x16x32_bf16 v[4:7], v[168:171], v[232:235], v[4:7]
	v_mfma_f32_16x16x32_bf16 v[0:3], v[176:179], v[232:235], v[0:3]
	s_setprio 0
	s_barrier
	s_add_i32 s4, 0, 0x18000
	v_add_u32_e32 v128, s4, v145
	s_add_i32 s64, 0, 0x1c000
	ds_read_b128 v[148:151], v128
	ds_read_b128 v[152:155], v128 offset:1024
	ds_read_b128 v[156:159], v128 offset:2048
	ds_read_b128 v[160:163], v128 offset:3072
	v_add_u32_e32 v128, s64, v145
	ds_read_b128 v[164:167], v128
	ds_read_b128 v[168:171], v128 offset:1024
	ds_read_b128 v[172:175], v128 offset:2048
	ds_read_b128 v[176:179], v128 offset:3072
	s_add_u32 s16, s16, s10
	s_addc_u32 s17, s17, s11
	s_mov_b32 m0, s37
	v_lshl_add_u64 v[246:247], s[16:17], 0, v[136:137]
	ds_read_b128 v[180:183], v147 offset:32768
	ds_read_b128 v[208:211], v147 offset:33792
	ds_read_b128 v[212:215], v147 offset:34816
	ds_read_b128 v[216:219], v147 offset:35840
	ds_read_b128 v[220:223], v147 offset:36864
	ds_read_b128 v[224:227], v147 offset:37888
	ds_read_b128 v[228:231], v147 offset:38912
	ds_read_b128 v[232:235], v147 offset:39936
	global_load_lds_dwordx4 v[246:247], off
	v_lshl_add_u64 v[246:247], v[246:247], 0, s[8:9]
	s_mov_b32 m0, s38
	s_nop 0
	global_load_lds_dwordx4 v[246:247], off
	s_waitcnt vmcnt(8)
	s_waitcnt lgkmcnt(0)
	s_barrier
	s_setprio 1
	s_waitcnt lgkmcnt(0)
	v_mfma_f32_16x16x32_bf16 v[120:123], v[148:151], v[180:183], v[120:123]
	v_mfma_f32_16x16x32_bf16 v[124:127], v[156:159], v[180:183], v[124:127]
	v_mfma_f32_16x16x32_bf16 v[108:111], v[148:151], v[212:215], v[108:111]
	v_mfma_f32_16x16x32_bf16 v[104:107], v[156:159], v[212:215], v[104:107]
	v_mfma_f32_16x16x32_bf16 v[92:95], v[148:151], v[220:223], v[92:95]
	v_mfma_f32_16x16x32_bf16 v[88:91], v[156:159], v[220:223], v[88:91]
	v_mfma_f32_16x16x32_bf16 v[76:79], v[148:151], v[228:231], v[76:79]
	v_mfma_f32_16x16x32_bf16 v[72:75], v[156:159], v[228:231], v[72:75]
	v_mfma_f32_16x16x32_bf16 v[120:123], v[152:155], v[208:211], v[120:123]
	v_mfma_f32_16x16x32_bf16 v[124:127], v[160:163], v[208:211], v[124:127]
	v_mfma_f32_16x16x32_bf16 v[108:111], v[152:155], v[216:219], v[108:111]
	v_mfma_f32_16x16x32_bf16 v[104:107], v[160:163], v[216:219], v[104:107]
	v_mfma_f32_16x16x32_bf16 v[92:95], v[152:155], v[224:227], v[92:95]
	v_mfma_f32_16x16x32_bf16 v[88:91], v[160:163], v[224:227], v[88:91]
	v_mfma_f32_16x16x32_bf16 v[76:79], v[152:155], v[232:235], v[76:79]
	v_mfma_f32_16x16x32_bf16 v[72:75], v[160:163], v[232:235], v[72:75]
	s_setprio 0
	s_setprio 1
	v_mfma_f32_16x16x32_bf16 v[116:119], v[164:167], v[180:183], v[116:119]
	v_mfma_f32_16x16x32_bf16 v[112:115], v[172:175], v[180:183], v[112:115]
	v_mfma_f32_16x16x32_bf16 v[100:103], v[164:167], v[212:215], v[100:103]
	v_mfma_f32_16x16x32_bf16 v[96:99], v[172:175], v[212:215], v[96:99]
	v_mfma_f32_16x16x32_bf16 v[84:87], v[164:167], v[220:223], v[84:87]
	v_mfma_f32_16x16x32_bf16 v[80:83], v[172:175], v[220:223], v[80:83]
	v_mfma_f32_16x16x32_bf16 v[68:71], v[164:167], v[228:231], v[68:71]
	v_mfma_f32_16x16x32_bf16 v[64:67], v[172:175], v[228:231], v[64:67]
	v_mfma_f32_16x16x32_bf16 v[116:119], v[168:171], v[208:211], v[116:119]
	v_mfma_f32_16x16x32_bf16 v[112:115], v[176:179], v[208:211], v[112:115]
	v_mfma_f32_16x16x32_bf16 v[100:103], v[168:171], v[216:219], v[100:103]
	v_mfma_f32_16x16x32_bf16 v[96:99], v[176:179], v[216:219], v[96:99]
	v_mfma_f32_16x16x32_bf16 v[84:87], v[168:171], v[224:227], v[84:87]
	v_mfma_f32_16x16x32_bf16 v[80:83], v[176:179], v[224:227], v[80:83]
	v_mfma_f32_16x16x32_bf16 v[68:71], v[168:171], v[232:235], v[68:71]
	v_mfma_f32_16x16x32_bf16 v[64:67], v[176:179], v[232:235], v[64:67]
	s_setprio 0
	s_barrier
; #define PG8_STAGE(bufoff, gbase, voff) do { _Pragma("unroll") for (int _i = 0; _i < 2; ++_i) \
;         __builtin_amdgcn_global_load_lds((const unsigned*)((const char*)(gbase) + _i * rdelta + (voff)), (LAS unsigned*)(lds + (bufoff) + ldsw + _i * 8192), 16, 0, 0); } while (0)
; #define PG8_LDA(dst, b, h) do { _Pragma("unroll") for (int m = 0; m < 4; ++m) _Pragma("unroll") for (int k = 0; k < 2; ++k) dst[m][k] = *(const LAS bf16x8*)(lds + PG8_SA(b, h) + aoff + m * 2048 + k * 1024); } while (0)
; #define PG8_MMA(ai, bj, At, Bt) do { __builtin_amdgcn_s_setprio(1); _Pragma("unroll") for (int m = 0; m < 4; ++m) _Pragma("unroll") for (int n = 0; n < 2; ++n) _Pragma("unroll") for (int k = 0; k < 2; ++k) \
;         acc[ai][bj][m][n] = __builtin_amdgcn_mfma_f32_16x16x32_bf16(Bt[n][k], At[m][k], acc[ai][bj][m][n], 0, 0, 0); __builtin_amdgcn_s_setprio(0); } while (0)
; #define PG8_WAIT_V(n) asm volatile("s_waitcnt vmcnt(" #n ")" ::: "memory")
; #define PG8_WAIT_L(n) asm volatile("s_waitcnt lgkmcnt(" #n ")" ::: "memory")
; #define PG8_BAR __builtin_amdgcn_s_barrier()
; #define PG8_SCHED __builtin_amdgcn_sched_barrier(0)
; template <class Epi, class Sched, bool ALIGN_EPI, bool SP2>
; __device__ __forceinline__ void gemm_phase(LAS unsigned char* lds, const Gemm g, const Sched& S, const Epi& E) {
;     ...
;             PG8_LDA(At, 1, 1); PG8_STAGE(PG8_SB(1, 0), b3, voffB); PG8_STAGE(PG8_SB(1, 1), b3 + hstep, voffB); PG8_STAGE(PG8_SA(1, 0), a3, voffA);
;             PG8_WAIT_V(8); PG8_WAIT_L(0); PG8_BAR; PG8_MMA(1, 0, At, B0); PG8_MMA(1, 1, At, B1); PG8_BAR; PG8_SCHED;
;         }
	s_add_i32 s4, s4, s34
	v_lshl_add_u64 v[142:143], v[142:143], 0, s[30:31]
	s_mov_b32 m0, s4
	ds_read_b128 v[180:183], v147 offset:49152
	ds_read_b128 v[208:211], v147 offset:50176
	ds_read_b128 v[212:215], v147 offset:51200
	ds_read_b128 v[216:219], v147 offset:52224
	ds_read_b128 v[220:223], v147 offset:53248
	ds_read_b128 v[224:227], v147 offset:54272
	ds_read_b128 v[228:231], v147 offset:55296
	ds_read_b128 v[232:235], v147 offset:56320
	global_load_lds_dwordx4 v[142:143], off
	v_lshl_add_u64 v[142:143], v[236:237], 0, s[30:31]
	s_add_i32 m0, s4, 0x2000
	s_add_i32 s4, s64, s34
	global_load_lds_dwordx4 v[142:143], off
	v_lshl_add_u64 v[142:143], v[238:239], 0, s[30:31]
	s_mov_b32 m0, s4
	s_nop 0
	global_load_lds_dwordx4 v[142:143], off
	v_lshl_add_u64 v[142:143], v[240:241], 0, s[30:31]
	s_add_i32 m0, s4, 0x2000
	s_nop 0
	global_load_lds_dwordx4 v[142:143], off
	v_lshl_add_u64 v[142:143], v[242:243], 0, s[30:31]
	s_mov_b32 m0, s40
	s_nop 0
	global_load_lds_dwordx4 v[142:143], off
	v_lshl_add_u64 v[142:143], v[244:245], 0, s[30:31]
	s_mov_b32 m0, s41
	s_nop 0
	global_load_lds_dwordx4 v[142:143], off
	s_waitcnt vmcnt(8)
	s_waitcnt lgkmcnt(0)
	s_barrier
	s_setprio 1
	s_waitcnt lgkmcnt(0)
	v_mfma_f32_16x16x32_bf16 v[60:63], v[148:151], v[180:183], v[60:63]
	v_mfma_f32_16x16x32_bf16 v[56:59], v[156:159], v[180:183], v[56:59]
	v_mfma_f32_16x16x32_bf16 v[44:47], v[148:151], v[212:215], v[44:47]
	v_mfma_f32_16x16x32_bf16 v[40:43], v[156:159], v[212:215], v[40:43]
	v_mfma_f32_16x16x32_bf16 v[28:31], v[148:151], v[220:223], v[28:31]
	v_mfma_f32_16x16x32_bf16 v[24:27], v[156:159], v[220:223], v[24:27]
	v_mfma_f32_16x16x32_bf16 v[12:15], v[148:151], v[228:231], v[12:15]
	v_mfma_f32_16x16x32_bf16 v[8:11], v[156:159], v[228:231], v[8:11]
	v_mfma_f32_16x16x32_bf16 v[60:63], v[152:155], v[208:211], v[60:63]
	v_mfma_f32_16x16x32_bf16 v[56:59], v[160:163], v[208:211], v[56:59]
	v_mfma_f32_16x16x32_bf16 v[44:47], v[152:155], v[216:219], v[44:47]
	v_mfma_f32_16x16x32_bf16 v[40:43], v[160:163], v[216:219], v[40:43]
	v_mfma_f32_16x16x32_bf16 v[28:31], v[152:155], v[224:227], v[28:31]
	v_mfma_f32_16x16x32_bf16 v[24:27], v[160:163], v[224:227], v[24:27]
	v_mfma_f32_16x16x32_bf16 v[12:15], v[152:155], v[232:235], v[12:15]
	v_mfma_f32_16x16x32_bf16 v[8:11], v[160:163], v[232:235], v[8:11]
	s_setprio 0
	s_setprio 1
	v_mfma_f32_16x16x32_bf16 v[52:55], v[164:167], v[180:183], v[52:55]
	v_mfma_f32_16x16x32_bf16 v[48:51], v[172:175], v[180:183], v[48:51]
	v_mfma_f32_16x16x32_bf16 v[36:39], v[164:167], v[212:215], v[36:39]
	v_mfma_f32_16x16x32_bf16 v[32:35], v[172:175], v[212:215], v[32:35]
	v_mfma_f32_16x16x32_bf16 v[20:23], v[164:167], v[220:223], v[20:23]
	v_mfma_f32_16x16x32_bf16 v[16:19], v[172:175], v[220:223], v[16:19]
	v_mfma_f32_16x16x32_bf16 v[4:7], v[164:167], v[228:231], v[4:7]
	v_mfma_f32_16x16x32_bf16 v[0:3], v[172:175], v[228:231], v[0:3]
	v_mfma_f32_16x16x32_bf16 v[52:55], v[168:171], v[208:211], v[52:55]
	v_mfma_f32_16x16x32_bf16 v[48:51], v[176:179], v[208:211], v[48:51]
	v_mfma_f32_16x16x32_bf16 v[36:39], v[168:171], v[216:219], v[36:39]
	v_mfma_f32_16x16x32_bf16 v[32:35], v[176:179], v[216:219], v[32:35]
	v_mfma_f32_16x16x32_bf16 v[20:23], v[168:171], v[224:227], v[20:23]
	v_mfma_f32_16x16x32_bf16 v[16:19], v[176:179], v[224:227], v[16:19]
	v_mfma_f32_16x16x32_bf16 v[4:7], v[168:171], v[232:235], v[4:7]
	v_mfma_f32_16x16x32_bf16 v[0:3], v[176:179], v[232:235], v[0:3]
	s_setprio 0
	s_add_u32 s14, s14, 0x100
	s_addc_u32 s15, s15, 0
	s_add_u32 s18, s18, 0x100
	s_addc_u32 s19, s19, 0
	s_cmp_ge_i32 s63, s56
	s_mov_b32 s4, s63
	s_barrier
	s_cbranch_scc0 .LBB0_862

; #define PG8_STAGE(bufoff, gbase, voff) do { _Pragma("unroll") for (int _i = 0; _i < 2; ++_i) \
;         __builtin_amdgcn_global_load_lds((const unsigned*)((const char*)(gbase) + _i * rdelta + (voff)), (LAS unsigned*)(lds + (bufoff) + ldsw + _i * 8192), 16, 0, 0); } while (0)
; #define PG8_LDA(dst, b, h) do { _Pragma("unroll") for (int m = 0; m < 4; ++m) _Pragma("unroll") for (int k = 0; k < 2; ++k) dst[m][k] = *(const LAS bf16x8*)(lds + PG8_SA(b, h) + aoff + m * 2048 + k * 1024); } while (0)
; #define PG8_LDB(dst, b, h) do { _Pragma("unroll") for (int n = 0; n < 2; ++n) _Pragma("unroll") for (int k = 0; k < 2; ++k) dst[n][k] = *(const LAS bf16x8*)(lds + PG8_SB(b, h) + boff + n * 2048 + k * 1024); } while (0)
; #define PG8_MMA(ai, bj, At, Bt) do { __builtin_amdgcn_s_setprio(1); _Pragma("unroll") for (int m = 0; m < 4; ++m) _Pragma("unroll") for (int n = 0; n < 2; ++n) _Pragma("unroll") for (int k = 0; k < 2; ++k) \
;         acc[ai][bj][m][n] = __builtin_amdgcn_mfma_f32_16x16x32_bf16(Bt[n][k], At[m][k], acc[ai][bj][m][n], 0, 0, 0); __builtin_amdgcn_s_setprio(0); } while (0)
; #define PG8_WAIT_V(n) asm volatile("s_waitcnt vmcnt(" #n ")" ::: "memory")
; #define PG8_WAIT_L(n) asm volatile("s_waitcnt lgkmcnt(" #n ")" ::: "memory")
; template <class Epi, class Sched, bool ALIGN_EPI, bool SP2>
; __device__ __forceinline__ void gemm_phase(LAS unsigned char* lds, const Gemm g, const Sched& S, const Epi& E) {
;     ...
;         for (int t = 0; t < nt; t += 2) {
;             if constexpr (Epi::HOOK) { if (t == Epi::T1 || t == Epi::T2) E.hook(acc, ui, t, wr, fr); }
;             const bool last = (t == nt - 2);
;             const char* a1 = cA + (size_t)(t + 1) * kstep;
;             const char* a2 = last ? nA : cA + (size_t)(t + 2) * kstep; const char* b2 = last ? nB : cB + (size_t)(t + 2) * kstep;
;             const char* a3 = a2 + kstep; const char* b3 = b2 + kstep;
;             PG8_LDB(B0, 0, 0); PG8_LDB(B1, 0, 1); PG8_SCHED; PG8_LDA(At, 0, 0); PG8_STAGE(PG8_SA(1, 1), a1 + hstep, voffA);
;             PG8_WAIT_V(8); PG8_WAIT_L(0); PG8_BAR; PG8_MMA(0, 0, At, B0); PG8_MMA(0, 1, At, B1); PG8_BAR; PG8_SCHED;
;             PG8_LDA(At, 0, 1); PG8_STAGE(PG8_SB(0, 0), b2, voffB); PG8_STAGE(PG8_SB(0, 1), b2 + hstep, voffB); PG8_STAGE(PG8_SA(0, 0), a2, voffA);
;             PG8_WAIT_V(8); PG8_WAIT_L(0); PG8_BAR; PG8_MMA(1, 0, At, B0); PG8_MMA(1, 1, At, B1); PG8_BAR; PG8_SCHED;
.LBB0_1169:
	s_add_i32 s69, s4, 2
	s_add_u32 s16, s14, 0x80
	s_addc_u32 s17, s15, 0
	s_add_i32 s72, 0, 0x10000
	s_cmp_eq_u32 s63, s4
	s_cselect_b32 s17, s7, s17
	s_cselect_b32 s16, s6, s16
	v_add_u32_e32 v144, s72, v147
	s_cselect_b32 s71, s61, s19
	s_cselect_b32 s70, s60, s18
	s_add_i32 s4, 0, 0x14000
	ds_read_b128 v[140:143], v144
	ds_read_b128 v[150:153], v144 offset:1024
	ds_read_b128 v[154:157], v144 offset:2048
	ds_read_b128 v[158:161], v144 offset:3072
	v_add_u32_e32 v144, s4, v147
	ds_read_b128 v[162:165], v144
	ds_read_b128 v[166:169], v144 offset:1024
	ds_read_b128 v[170:173], v144 offset:2048
	ds_read_b128 v[174:177], v144 offset:3072
	v_lshl_add_u64 v[144:145], s[14:15], 0, v[136:137]
	s_add_i32 m0, s37, 0xc000
	ds_read_b128 v[178:181], v149
	ds_read_b128 v[208:211], v149 offset:1024
	ds_read_b128 v[212:215], v149 offset:2048
	ds_read_b128 v[216:219], v149 offset:3072
	ds_read_b128 v[220:223], v149 offset:4096
	ds_read_b128 v[224:227], v149 offset:5120
	ds_read_b128 v[228:231], v149 offset:6144
	ds_read_b128 v[232:235], v149 offset:7168
	global_load_lds_dwordx4 v[144:145], off
	v_lshl_add_u64 v[144:145], s[14:15], 0, v[138:139]
	s_add_i32 m0, s37, 0xe000
	s_nop 0
	global_load_lds_dwordx4 v[144:145], off
	s_waitcnt vmcnt(8)
	s_waitcnt lgkmcnt(0)
	s_barrier
	s_setprio 1
	s_waitcnt lgkmcnt(0)
	v_mfma_f32_16x16x32_bf16 v[120:123], v[140:143], v[178:181], v[120:123]
	v_mfma_f32_16x16x32_bf16 v[124:127], v[154:157], v[178:181], v[124:127]
	v_mfma_f32_16x16x32_bf16 v[108:111], v[140:143], v[212:215], v[108:111]
	v_mfma_f32_16x16x32_bf16 v[104:107], v[154:157], v[212:215], v[104:107]
	v_mfma_f32_16x16x32_bf16 v[92:95], v[140:143], v[220:223], v[92:95]
	v_mfma_f32_16x16x32_bf16 v[88:91], v[154:157], v[220:223], v[88:91]
	v_mfma_f32_16x16x32_bf16 v[76:79], v[140:143], v[228:231], v[76:79]
	v_mfma_f32_16x16x32_bf16 v[72:75], v[154:157], v[228:231], v[72:75]
	v_mfma_f32_16x16x32_bf16 v[120:123], v[150:153], v[208:211], v[120:123]
	v_mfma_f32_16x16x32_bf16 v[124:127], v[158:161], v[208:211], v[124:127]
	v_mfma_f32_16x16x32_bf16 v[108:111], v[150:153], v[216:219], v[108:111]
	v_mfma_f32_16x16x32_bf16 v[104:107], v[158:161], v[216:219], v[104:107]
	v_mfma_f32_16x16x32_bf16 v[92:95], v[150:153], v[224:227], v[92:95]
	v_mfma_f32_16x16x32_bf16 v[88:91], v[158:161], v[224:227], v[88:91]
	v_mfma_f32_16x16x32_bf16 v[76:79], v[150:153], v[232:235], v[76:79]
	v_mfma_f32_16x16x32_bf16 v[72:75], v[158:161], v[232:235], v[72:75]
	s_setprio 0
	s_setprio 1
	v_mfma_f32_16x16x32_bf16 v[116:119], v[162:165], v[178:181], v[116:119]
	v_mfma_f32_16x16x32_bf16 v[112:115], v[170:173], v[178:181], v[112:115]
	v_mfma_f32_16x16x32_bf16 v[100:103], v[162:165], v[212:215], v[100:103]
	v_mfma_f32_16x16x32_bf16 v[96:99], v[170:173], v[212:215], v[96:99]
	v_mfma_f32_16x16x32_bf16 v[84:87], v[162:165], v[220:223], v[84:87]
	v_mfma_f32_16x16x32_bf16 v[80:83], v[170:173], v[220:223], v[80:83]
	v_mfma_f32_16x16x32_bf16 v[68:71], v[162:165], v[228:231], v[68:71]
	v_mfma_f32_16x16x32_bf16 v[64:67], v[170:173], v[228:231], v[64:67]
	v_mfma_f32_16x16x32_bf16 v[116:119], v[166:169], v[208:211], v[116:119]
	v_mfma_f32_16x16x32_bf16 v[112:115], v[174:177], v[208:211], v[112:115]
	v_mfma_f32_16x16x32_bf16 v[100:103], v[166:169], v[216:219], v[100:103]
	v_mfma_f32_16x16x32_bf16 v[96:99], v[174:177], v[216:219], v[96:99]
	v_mfma_f32_16x16x32_bf16 v[84:87], v[166:169], v[224:227], v[84:87]
	v_mfma_f32_16x16x32_bf16 v[80:83], v[174:177], v[224:227], v[80:83]
	v_mfma_f32_16x16x32_bf16 v[68:71], v[166:169], v[232:235], v[68:71]
	v_mfma_f32_16x16x32_bf16 v[64:67], v[174:177], v[232:235], v[64:67]
	s_setprio 0
	s_barrier
	s_add_i32 s72, s72, s36
	v_lshl_add_u64 v[144:145], s[70:71], 0, v[128:129]
	s_mov_b32 m0, s72
	ds_read_b128 v[178:181], v149 offset:16384
	ds_read_b128 v[208:211], v149 offset:17408
	ds_read_b128 v[212:215], v149 offset:18432
	ds_read_b128 v[216:219], v149 offset:19456
	ds_read_b128 v[220:223], v149 offset:20480
	ds_read_b128 v[224:227], v149 offset:21504
	ds_read_b128 v[228:231], v149 offset:22528
	ds_read_b128 v[232:235], v149 offset:23552
	global_load_lds_dwordx4 v[144:145], off
	s_add_i32 m0, s72, 0x2000
	s_add_u32 s70, s70, s10
	v_lshl_add_u64 v[182:183], v[144:145], 0, s[8:9]
	s_addc_u32 s71, s71, s11
	s_add_i32 s4, s4, s36
	global_load_lds_dwordx4 v[182:183], off
	v_lshl_add_u64 v[236:237], s[70:71], 0, v[128:129]
	s_mov_b32 m0, s4
	v_lshl_add_u64 v[238:239], v[236:237], 0, s[8:9]
	global_load_lds_dwordx4 v[236:237], off
	s_add_i32 m0, s4, 0x2000
	v_lshl_add_u64 v[240:241], s[16:17], 0, v[130:131]
	global_load_lds_dwordx4 v[238:239], off
	s_mov_b32 m0, s37
	v_lshl_add_u64 v[242:243], v[240:241], 0, s[8:9]
	global_load_lds_dwordx4 v[240:241], off
	s_mov_b32 m0, s40
	s_nop 0
	global_load_lds_dwordx4 v[242:243], off
	s_waitcnt vmcnt(8)
	s_waitcnt lgkmcnt(0)
	s_barrier
; #define PG8_STAGE(bufoff, gbase, voff) do { _Pragma("unroll") for (int _i = 0; _i < 2; ++_i) \
;         __builtin_amdgcn_global_load_lds((const unsigned*)((const char*)(gbase) + _i * rdelta + (voff)), (LAS unsigned*)(lds + (bufoff) + ldsw + _i * 8192), 16, 0, 0); } while (0)
; #define PG8_LDA(dst, b, h) do { _Pragma("unroll") for (int m = 0; m < 4; ++m) _Pragma("unroll") for (int k = 0; k < 2; ++k) dst[m][k] = *(const LAS bf16x8*)(lds + PG8_SA(b, h) + aoff + m * 2048 + k * 1024); } while (0)
; #define PG8_LDB(dst, b, h) do { _Pragma("unroll") for (int n = 0; n < 2; ++n) _Pragma("unroll") for (int k = 0; k < 2; ++k) dst[n][k] = *(const LAS bf16x8*)(lds + PG8_SB(b, h) + boff + n * 2048 + k * 1024); } while (0)
; #define PG8_MMA(ai, bj, At, Bt) do { __builtin_amdgcn_s_setprio(1); _Pragma("unroll") for (int m = 0; m < 4; ++m) _Pragma("unroll") for (int n = 0; n < 2; ++n) _Pragma("unroll") for (int k = 0; k < 2; ++k) \
;         acc[ai][bj][m][n] = __builtin_amdgcn_mfma_f32_16x16x32_bf16(Bt[n][k], At[m][k], acc[ai][bj][m][n], 0, 0, 0); __builtin_amdgcn_s_setprio(0); } while (0)
; #define PG8_WAIT_V(n) asm volatile("s_waitcnt vmcnt(" #n ")" ::: "memory")
; #define PG8_WAIT_L(n) asm volatile("s_waitcnt lgkmcnt(" #n ")" ::: "memory")
; #define PG8_BAR __builtin_amdgcn_s_barrier()
; #define PG8_SCHED __builtin_amdgcn_sched_barrier(0)
; template <class Epi, class Sched, bool ALIGN_EPI, bool SP2>
; __device__ __forceinline__ void gemm_phase(LAS unsigned char* lds, const Gemm g, const Sched& S, const Epi& E) {
;     ...
;             PG8_WAIT_V(8); PG8_WAIT_L(0); PG8_BAR; PG8_MMA(1, 0, At, B0); PG8_MMA(1, 1, At, B1); PG8_BAR; PG8_SCHED;
;             PG8_LDB(B0, 1, 0); PG8_LDB(B1, 1, 1); PG8_SCHED; PG8_LDA(At, 1, 0); PG8_STAGE(PG8_SA(0, 1), a2 + hstep, voffA);
;             PG8_WAIT_V(8); PG8_WAIT_L(0); PG8_BAR; PG8_MMA(0, 0, At, B0); PG8_MMA(0, 1, At, B1); PG8_BAR; PG8_SCHED;
	s_setprio 1
	s_waitcnt lgkmcnt(0)
	v_mfma_f32_16x16x32_bf16 v[60:63], v[140:143], v[178:181], v[60:63]
	v_mfma_f32_16x16x32_bf16 v[56:59], v[154:157], v[178:181], v[56:59]
	v_mfma_f32_16x16x32_bf16 v[44:47], v[140:143], v[212:215], v[44:47]
	v_mfma_f32_16x16x32_bf16 v[40:43], v[154:157], v[212:215], v[40:43]
	v_mfma_f32_16x16x32_bf16 v[28:31], v[140:143], v[220:223], v[28:31]
	v_mfma_f32_16x16x32_bf16 v[24:27], v[154:157], v[220:223], v[24:27]
	v_mfma_f32_16x16x32_bf16 v[12:15], v[140:143], v[228:231], v[12:15]
	v_mfma_f32_16x16x32_bf16 v[8:11], v[154:157], v[228:231], v[8:11]
	v_mfma_f32_16x16x32_bf16 v[60:63], v[150:153], v[208:211], v[60:63]
	v_mfma_f32_16x16x32_bf16 v[56:59], v[158:161], v[208:211], v[56:59]
	v_mfma_f32_16x16x32_bf16 v[44:47], v[150:153], v[216:219], v[44:47]
	v_mfma_f32_16x16x32_bf16 v[40:43], v[158:161], v[216:219], v[40:43]
	v_mfma_f32_16x16x32_bf16 v[28:31], v[150:153], v[224:227], v[28:31]
	v_mfma_f32_16x16x32_bf16 v[24:27], v[158:161], v[224:227], v[24:27]
	v_mfma_f32_16x16x32_bf16 v[12:15], v[150:153], v[232:235], v[12:15]
	v_mfma_f32_16x16x32_bf16 v[8:11], v[158:161], v[232:235], v[8:11]
	s_setprio 0
	s_setprio 1
	v_mfma_f32_16x16x32_bf16 v[52:55], v[162:165], v[178:181], v[52:55]
	v_mfma_f32_16x16x32_bf16 v[48:51], v[170:173], v[178:181], v[48:51]
	v_mfma_f32_16x16x32_bf16 v[36:39], v[162:165], v[212:215], v[36:39]
	v_mfma_f32_16x16x32_bf16 v[32:35], v[170:173], v[212:215], v[32:35]
	v_mfma_f32_16x16x32_bf16 v[20:23], v[162:165], v[220:223], v[20:23]
	v_mfma_f32_16x16x32_bf16 v[16:19], v[170:173], v[220:223], v[16:19]
	v_mfma_f32_16x16x32_bf16 v[4:7], v[162:165], v[228:231], v[4:7]
	v_mfma_f32_16x16x32_bf16 v[0:3], v[170:173], v[228:231], v[0:3]
	v_mfma_f32_16x16x32_bf16 v[52:55], v[166:169], v[208:211], v[52:55]
	v_mfma_f32_16x16x32_bf16 v[48:51], v[174:177], v[208:211], v[48:51]
	v_mfma_f32_16x16x32_bf16 v[36:39], v[166:169], v[216:219], v[36:39]
	v_mfma_f32_16x16x32_bf16 v[32:35], v[174:177], v[216:219], v[32:35]
	v_mfma_f32_16x16x32_bf16 v[20:23], v[166:169], v[224:227], v[20:23]
	v_mfma_f32_16x16x32_bf16 v[16:19], v[174:177], v[224:227], v[16:19]
	v_mfma_f32_16x16x32_bf16 v[4:7], v[166:169], v[232:235], v[4:7]
	v_mfma_f32_16x16x32_bf16 v[0:3], v[174:177], v[232:235], v[0:3]
	s_setprio 0
	s_barrier
	s_add_i32 s4, 0, 0x18000
	s_add_i32 s70, 0, 0x1c000
	v_add_u32_e32 v158, s4, v147
	v_add_u32_e32 v174, s70, v147
	ds_read_b128 v[140:143], v158
	ds_read_b128 v[150:153], v158 offset:1024
	ds_read_b128 v[154:157], v158 offset:2048
	ds_read_b128 v[158:161], v158 offset:3072
	ds_read_b128 v[162:165], v174
	ds_read_b128 v[166:169], v174 offset:1024
	ds_read_b128 v[170:173], v174 offset:2048
	ds_read_b128 v[174:177], v174 offset:3072
	s_add_u32 s16, s16, s10
	s_addc_u32 s17, s17, s11
	s_mov_b32 m0, s41
	v_lshl_add_u64 v[244:245], s[16:17], 0, v[130:131]
	ds_read_b128 v[178:181], v149 offset:32768
	ds_read_b128 v[208:211], v149 offset:33792
	ds_read_b128 v[212:215], v149 offset:34816
	ds_read_b128 v[216:219], v149 offset:35840
	ds_read_b128 v[220:223], v149 offset:36864
	ds_read_b128 v[224:227], v149 offset:37888
	ds_read_b128 v[228:231], v149 offset:38912
	ds_read_b128 v[232:235], v149 offset:39936
	global_load_lds_dwordx4 v[244:245], off
	v_lshl_add_u64 v[244:245], v[244:245], 0, s[8:9]
	s_mov_b32 m0, s62
	s_nop 0
	global_load_lds_dwordx4 v[244:245], off
	s_waitcnt vmcnt(8)
	s_waitcnt lgkmcnt(0)
	s_barrier
	s_setprio 1
	s_waitcnt lgkmcnt(0)
	v_mfma_f32_16x16x32_bf16 v[120:123], v[140:143], v[178:181], v[120:123]
	v_mfma_f32_16x16x32_bf16 v[124:127], v[154:157], v[178:181], v[124:127]
	v_mfma_f32_16x16x32_bf16 v[108:111], v[140:143], v[212:215], v[108:111]
	v_mfma_f32_16x16x32_bf16 v[104:107], v[154:157], v[212:215], v[104:107]
	v_mfma_f32_16x16x32_bf16 v[92:95], v[140:143], v[220:223], v[92:95]
	v_mfma_f32_16x16x32_bf16 v[88:91], v[154:157], v[220:223], v[88:91]
	v_mfma_f32_16x16x32_bf16 v[76:79], v[140:143], v[228:231], v[76:79]
	v_mfma_f32_16x16x32_bf16 v[72:75], v[154:157], v[228:231], v[72:75]
	v_mfma_f32_16x16x32_bf16 v[120:123], v[150:153], v[208:211], v[120:123]
	v_mfma_f32_16x16x32_bf16 v[124:127], v[158:161], v[208:211], v[124:127]
	v_mfma_f32_16x16x32_bf16 v[108:111], v[150:153], v[216:219], v[108:111]
	v_mfma_f32_16x16x32_bf16 v[104:107], v[158:161], v[216:219], v[104:107]
	v_mfma_f32_16x16x32_bf16 v[92:95], v[150:153], v[224:227], v[92:95]
	v_mfma_f32_16x16x32_bf16 v[88:91], v[158:161], v[224:227], v[88:91]
	v_mfma_f32_16x16x32_bf16 v[76:79], v[150:153], v[232:235], v[76:79]
	v_mfma_f32_16x16x32_bf16 v[72:75], v[158:161], v[232:235], v[72:75]
	s_setprio 0
	s_setprio 1
	v_mfma_f32_16x16x32_bf16 v[116:119], v[162:165], v[178:181], v[116:119]
	v_mfma_f32_16x16x32_bf16 v[112:115], v[170:173], v[178:181], v[112:115]
	v_mfma_f32_16x16x32_bf16 v[100:103], v[162:165], v[212:215], v[100:103]
	v_mfma_f32_16x16x32_bf16 v[96:99], v[170:173], v[212:215], v[96:99]
	v_mfma_f32_16x16x32_bf16 v[84:87], v[162:165], v[220:223], v[84:87]
	v_mfma_f32_16x16x32_bf16 v[80:83], v[170:173], v[220:223], v[80:83]
	v_mfma_f32_16x16x32_bf16 v[68:71], v[162:165], v[228:231], v[68:71]
	v_mfma_f32_16x16x32_bf16 v[64:67], v[170:173], v[228:231], v[64:67]
	v_mfma_f32_16x16x32_bf16 v[116:119], v[166:169], v[208:211], v[116:119]
	v_mfma_f32_16x16x32_bf16 v[112:115], v[174:177], v[208:211], v[112:115]
	v_mfma_f32_16x16x32_bf16 v[100:103], v[166:169], v[216:219], v[100:103]
	v_mfma_f32_16x16x32_bf16 v[96:99], v[174:177], v[216:219], v[96:99]
	v_mfma_f32_16x16x32_bf16 v[84:87], v[166:169], v[224:227], v[84:87]
	v_mfma_f32_16x16x32_bf16 v[80:83], v[174:177], v[224:227], v[80:83]
	v_mfma_f32_16x16x32_bf16 v[68:71], v[166:169], v[232:235], v[68:71]
	v_mfma_f32_16x16x32_bf16 v[64:67], v[174:177], v[232:235], v[64:67]
	s_setprio 0
	s_barrier
; #define PG8_STAGE(bufoff, gbase, voff) do { _Pragma("unroll") for (int _i = 0; _i < 2; ++_i) \
;         __builtin_amdgcn_global_load_lds((const unsigned*)((const char*)(gbase) + _i * rdelta + (voff)), (LAS unsigned*)(lds + (bufoff) + ldsw + _i * 8192), 16, 0, 0); } while (0)
; #define PG8_LDA(dst, b, h) do { _Pragma("unroll") for (int m = 0; m < 4; ++m) _Pragma("unroll") for (int k = 0; k < 2; ++k) dst[m][k] = *(const LAS bf16x8*)(lds + PG8_SA(b, h) + aoff + m * 2048 + k * 1024); } while (0)
; #define PG8_MMA(ai, bj, At, Bt) do { __builtin_amdgcn_s_setprio(1); _Pragma("unroll") for (int m = 0; m < 4; ++m) _Pragma("unroll") for (int n = 0; n < 2; ++n) _Pragma("unroll") for (int k = 0; k < 2; ++k) \
;         acc[ai][bj][m][n] = __builtin_amdgcn_mfma_f32_16x16x32_bf16(Bt[n][k], At[m][k], acc[ai][bj][m][n], 0, 0, 0); __builtin_amdgcn_s_setprio(0); } while (0)
; #define PG8_WAIT_V(n) asm volatile("s_waitcnt vmcnt(" #n ")" ::: "memory")
; #define PG8_WAIT_L(n) asm volatile("s_waitcnt lgkmcnt(" #n ")" ::: "memory")
; #define PG8_BAR __builtin_amdgcn_s_barrier()
; #define PG8_SCHED __builtin_amdgcn_sched_barrier(0)
; template <class Epi, class Sched, bool ALIGN_EPI, bool SP2>
; __device__ __forceinline__ void gemm_phase(LAS unsigned char* lds, const Gemm g, const Sched& S, const Epi& E) {
;     ...
;             PG8_LDA(At, 1, 1); PG8_STAGE(PG8_SB(1, 0), b3, voffB); PG8_STAGE(PG8_SB(1, 1), b3 + hstep, voffB); PG8_STAGE(PG8_SA(1, 0), a3, voffA);
;             PG8_WAIT_V(8); PG8_WAIT_L(0); PG8_BAR; PG8_MMA(1, 0, At, B0); PG8_MMA(1, 1, At, B1); PG8_BAR; PG8_SCHED;
;         }
	s_add_i32 s4, s4, s36
	v_lshl_add_u64 v[144:145], v[144:145], 0, s[30:31]
	s_mov_b32 m0, s4
	ds_read_b128 v[178:181], v149 offset:49152
	ds_read_b128 v[208:211], v149 offset:50176
	ds_read_b128 v[212:215], v149 offset:51200
	ds_read_b128 v[216:219], v149 offset:52224
	ds_read_b128 v[220:223], v149 offset:53248
	ds_read_b128 v[224:227], v149 offset:54272
	ds_read_b128 v[228:231], v149 offset:55296
	ds_read_b128 v[232:235], v149 offset:56320
	global_load_lds_dwordx4 v[144:145], off
	v_lshl_add_u64 v[144:145], v[182:183], 0, s[30:31]
	s_add_i32 m0, s4, 0x2000
	s_add_i32 s4, s70, s36
	global_load_lds_dwordx4 v[144:145], off
	v_lshl_add_u64 v[144:145], v[236:237], 0, s[30:31]
	s_mov_b32 m0, s4
	s_nop 0
	global_load_lds_dwordx4 v[144:145], off
	v_lshl_add_u64 v[144:145], v[238:239], 0, s[30:31]
	s_add_i32 m0, s4, 0x2000
	s_nop 0
	global_load_lds_dwordx4 v[144:145], off
	v_lshl_add_u64 v[144:145], v[240:241], 0, s[30:31]
	s_mov_b32 m0, s22
	s_nop 0
	global_load_lds_dwordx4 v[144:145], off
	v_lshl_add_u64 v[144:145], v[242:243], 0, s[30:31]
	s_mov_b32 m0, s23
	s_nop 0
	global_load_lds_dwordx4 v[144:145], off
	s_waitcnt vmcnt(8)
	s_waitcnt lgkmcnt(0)
	s_barrier
	s_setprio 1
	s_waitcnt lgkmcnt(0)
	v_mfma_f32_16x16x32_bf16 v[60:63], v[140:143], v[178:181], v[60:63]
	v_mfma_f32_16x16x32_bf16 v[56:59], v[154:157], v[178:181], v[56:59]
	v_mfma_f32_16x16x32_bf16 v[44:47], v[140:143], v[212:215], v[44:47]
	v_mfma_f32_16x16x32_bf16 v[40:43], v[154:157], v[212:215], v[40:43]
	v_mfma_f32_16x16x32_bf16 v[28:31], v[140:143], v[220:223], v[28:31]
	v_mfma_f32_16x16x32_bf16 v[24:27], v[154:157], v[220:223], v[24:27]
	v_mfma_f32_16x16x32_bf16 v[12:15], v[140:143], v[228:231], v[12:15]
	v_mfma_f32_16x16x32_bf16 v[8:11], v[154:157], v[228:231], v[8:11]
	v_mfma_f32_16x16x32_bf16 v[60:63], v[150:153], v[208:211], v[60:63]
	v_mfma_f32_16x16x32_bf16 v[56:59], v[158:161], v[208:211], v[56:59]
	v_mfma_f32_16x16x32_bf16 v[44:47], v[150:153], v[216:219], v[44:47]
	v_mfma_f32_16x16x32_bf16 v[40:43], v[158:161], v[216:219], v[40:43]
	v_mfma_f32_16x16x32_bf16 v[28:31], v[150:153], v[224:227], v[28:31]
	v_mfma_f32_16x16x32_bf16 v[24:27], v[158:161], v[224:227], v[24:27]
	v_mfma_f32_16x16x32_bf16 v[12:15], v[150:153], v[232:235], v[12:15]
	v_mfma_f32_16x16x32_bf16 v[8:11], v[158:161], v[232:235], v[8:11]
	s_setprio 0
	s_setprio 1
	v_mfma_f32_16x16x32_bf16 v[52:55], v[162:165], v[178:181], v[52:55]
	v_mfma_f32_16x16x32_bf16 v[48:51], v[170:173], v[178:181], v[48:51]
	v_mfma_f32_16x16x32_bf16 v[36:39], v[162:165], v[212:215], v[36:39]
	v_mfma_f32_16x16x32_bf16 v[32:35], v[170:173], v[212:215], v[32:35]
	v_mfma_f32_16x16x32_bf16 v[20:23], v[162:165], v[220:223], v[20:23]
	v_mfma_f32_16x16x32_bf16 v[16:19], v[170:173], v[220:223], v[16:19]
	v_mfma_f32_16x16x32_bf16 v[4:7], v[162:165], v[228:231], v[4:7]
	v_mfma_f32_16x16x32_bf16 v[0:3], v[170:173], v[228:231], v[0:3]
	v_mfma_f32_16x16x32_bf16 v[52:55], v[166:169], v[208:211], v[52:55]
	v_mfma_f32_16x16x32_bf16 v[48:51], v[174:177], v[208:211], v[48:51]
	v_mfma_f32_16x16x32_bf16 v[36:39], v[166:169], v[216:219], v[36:39]
	v_mfma_f32_16x16x32_bf16 v[32:35], v[174:177], v[216:219], v[32:35]
	v_mfma_f32_16x16x32_bf16 v[20:23], v[166:169], v[224:227], v[20:23]
	v_mfma_f32_16x16x32_bf16 v[16:19], v[174:177], v[224:227], v[16:19]
	v_mfma_f32_16x16x32_bf16 v[4:7], v[166:169], v[232:235], v[4:7]
	v_mfma_f32_16x16x32_bf16 v[0:3], v[174:177], v[232:235], v[0:3]
	s_setprio 0
	s_add_u32 s14, s14, 0x100
	s_addc_u32 s15, s15, 0
	s_add_u32 s18, s18, 0x100
	s_addc_u32 s19, s19, 0
	s_cmp_ge_i32 s69, s38
	s_mov_b32 s4, s69
	s_barrier
	s_cbranch_scc0 .LBB0_1169

; #define PG8_STAGE(bufoff, gbase, voff) do { _Pragma("unroll") for (int _i = 0; _i < 2; ++_i) \
;         __builtin_amdgcn_global_load_lds((const unsigned*)((const char*)(gbase) + _i * rdelta + (voff)), (LAS unsigned*)(lds + (bufoff) + ldsw + _i * 8192), 16, 0, 0); } while (0)
; #define PG8_LDA(dst, b, h) do { _Pragma("unroll") for (int m = 0; m < 4; ++m) _Pragma("unroll") for (int k = 0; k < 2; ++k) dst[m][k] = *(const LAS bf16x8*)(lds + PG8_SA(b, h) + aoff + m * 2048 + k * 1024); } while (0)
; #define PG8_LDB(dst, b, h) do { _Pragma("unroll") for (int n = 0; n < 2; ++n) _Pragma("unroll") for (int k = 0; k < 2; ++k) dst[n][k] = *(const LAS bf16x8*)(lds + PG8_SB(b, h) + boff + n * 2048 + k * 1024); } while (0)
; #define PG8_MMA(ai, bj, At, Bt) do { __builtin_amdgcn_s_setprio(1); _Pragma("unroll") for (int m = 0; m < 4; ++m) _Pragma("unroll") for (int n = 0; n < 2; ++n) _Pragma("unroll") for (int k = 0; k < 2; ++k) \
;         acc[ai][bj][m][n] = __builtin_amdgcn_mfma_f32_16x16x32_bf16(Bt[n][k], At[m][k], acc[ai][bj][m][n], 0, 0, 0); __builtin_amdgcn_s_setprio(0); } while (0)
; #define PG8_WAIT_V(n) asm volatile("s_waitcnt vmcnt(" #n ")" ::: "memory")
; #define PG8_WAIT_L(n) asm volatile("s_waitcnt lgkmcnt(" #n ")" ::: "memory")
; template <class Epi, class Sched, bool ALIGN_EPI, bool SP2>
; __device__ __forceinline__ void gemm_phase(LAS unsigned char* lds, const Gemm g, const Sched& S, const Epi& E) {
;     ...
;         for (int t = 0; t < nt; t += 2) {
;             if constexpr (Epi::HOOK) { if (t == Epi::T1 || t == Epi::T2) E.hook(acc, ui, t, wr, fr); }
;             const bool last = (t == nt - 2);
;             const char* a1 = cA + (size_t)(t + 1) * kstep;
;             const char* a2 = last ? nA : cA + (size_t)(t + 2) * kstep; const char* b2 = last ? nB : cB + (size_t)(t + 2) * kstep;
;             const char* a3 = a2 + kstep; const char* b3 = b2 + kstep;
;             PG8_LDB(B0, 0, 0); PG8_LDB(B1, 0, 1); PG8_SCHED; PG8_LDA(At, 0, 0); PG8_STAGE(PG8_SA(1, 1), a1 + hstep, voffA);
;             PG8_WAIT_V(8); PG8_WAIT_L(0); PG8_BAR; PG8_MMA(0, 0, At, B0); PG8_MMA(0, 1, At, B1); PG8_BAR; PG8_SCHED;
;             PG8_LDA(At, 0, 1); PG8_STAGE(PG8_SB(0, 0), b2, voffB); PG8_STAGE(PG8_SB(0, 1), b2 + hstep, voffB); PG8_STAGE(PG8_SA(0, 0), a2, voffA);
;             PG8_WAIT_V(8); PG8_WAIT_L(0); PG8_BAR; PG8_MMA(1, 0, At, B0); PG8_MMA(1, 1, At, B1); PG8_BAR; PG8_SCHED;
.LBB0_1365:
	s_add_i32 s65, s4, 2
	s_add_u32 s16, s14, 0x80
	s_addc_u32 s17, s15, 0
	s_add_i32 s68, 0, 0x10000
	s_cmp_eq_u32 s61, s4
	s_cselect_b32 s17, s7, s17
	s_cselect_b32 s16, s6, s16
	v_add_u32_e32 v128, s68, v145
	s_cselect_b32 s67, s57, s19
	s_cselect_b32 s66, s56, s18
	s_add_i32 s4, 0, 0x14000
	ds_read_b128 v[148:151], v128
	ds_read_b128 v[152:155], v128 offset:1024
	ds_read_b128 v[156:159], v128 offset:2048
	ds_read_b128 v[160:163], v128 offset:3072
	v_add_u32_e32 v128, s4, v145
	ds_read_b128 v[164:167], v128
	ds_read_b128 v[168:171], v128 offset:1024
	ds_read_b128 v[172:175], v128 offset:2048
	ds_read_b128 v[176:179], v128 offset:3072
	v_lshl_add_u64 v[142:143], s[14:15], 0, v[138:139]
	s_add_i32 m0, s35, 0xc000
	ds_read_b128 v[180:183], v147
	ds_read_b128 v[208:211], v147 offset:1024
	ds_read_b128 v[212:215], v147 offset:2048
	ds_read_b128 v[216:219], v147 offset:3072
	ds_read_b128 v[220:223], v147 offset:4096
	ds_read_b128 v[224:227], v147 offset:5120
	ds_read_b128 v[228:231], v147 offset:6144
	ds_read_b128 v[232:235], v147 offset:7168
	global_load_lds_dwordx4 v[142:143], off
	v_lshl_add_u64 v[142:143], s[14:15], 0, v[140:141]
	s_add_i32 m0, s35, 0xe000
	s_nop 0
	global_load_lds_dwordx4 v[142:143], off
	s_waitcnt vmcnt(8)
	s_waitcnt lgkmcnt(0)
	s_barrier
	s_setprio 1
	s_waitcnt lgkmcnt(0)
	v_mfma_f32_16x16x32_bf16 v[120:123], v[148:151], v[180:183], v[120:123]
	v_mfma_f32_16x16x32_bf16 v[124:127], v[156:159], v[180:183], v[124:127]
	v_mfma_f32_16x16x32_bf16 v[108:111], v[148:151], v[212:215], v[108:111]
	v_mfma_f32_16x16x32_bf16 v[104:107], v[156:159], v[212:215], v[104:107]
	v_mfma_f32_16x16x32_bf16 v[92:95], v[148:151], v[220:223], v[92:95]
	v_mfma_f32_16x16x32_bf16 v[88:91], v[156:159], v[220:223], v[88:91]
	v_mfma_f32_16x16x32_bf16 v[76:79], v[148:151], v[228:231], v[76:79]
	v_mfma_f32_16x16x32_bf16 v[72:75], v[156:159], v[228:231], v[72:75]
	v_mfma_f32_16x16x32_bf16 v[120:123], v[152:155], v[208:211], v[120:123]
	v_mfma_f32_16x16x32_bf16 v[124:127], v[160:163], v[208:211], v[124:127]
	v_mfma_f32_16x16x32_bf16 v[108:111], v[152:155], v[216:219], v[108:111]
	v_mfma_f32_16x16x32_bf16 v[104:107], v[160:163], v[216:219], v[104:107]
	v_mfma_f32_16x16x32_bf16 v[92:95], v[152:155], v[224:227], v[92:95]
	v_mfma_f32_16x16x32_bf16 v[88:91], v[160:163], v[224:227], v[88:91]
	v_mfma_f32_16x16x32_bf16 v[76:79], v[152:155], v[232:235], v[76:79]
	v_mfma_f32_16x16x32_bf16 v[72:75], v[160:163], v[232:235], v[72:75]
	s_setprio 0
	s_setprio 1
	v_mfma_f32_16x16x32_bf16 v[116:119], v[164:167], v[180:183], v[116:119]
	v_mfma_f32_16x16x32_bf16 v[112:115], v[172:175], v[180:183], v[112:115]
	v_mfma_f32_16x16x32_bf16 v[100:103], v[164:167], v[212:215], v[100:103]
	v_mfma_f32_16x16x32_bf16 v[96:99], v[172:175], v[212:215], v[96:99]
	v_mfma_f32_16x16x32_bf16 v[84:87], v[164:167], v[220:223], v[84:87]
	v_mfma_f32_16x16x32_bf16 v[80:83], v[172:175], v[220:223], v[80:83]
	v_mfma_f32_16x16x32_bf16 v[68:71], v[164:167], v[228:231], v[68:71]
	v_mfma_f32_16x16x32_bf16 v[64:67], v[172:175], v[228:231], v[64:67]
	v_mfma_f32_16x16x32_bf16 v[116:119], v[168:171], v[208:211], v[116:119]
	v_mfma_f32_16x16x32_bf16 v[112:115], v[176:179], v[208:211], v[112:115]
	v_mfma_f32_16x16x32_bf16 v[100:103], v[168:171], v[216:219], v[100:103]
	v_mfma_f32_16x16x32_bf16 v[96:99], v[176:179], v[216:219], v[96:99]
	v_mfma_f32_16x16x32_bf16 v[84:87], v[168:171], v[224:227], v[84:87]
	v_mfma_f32_16x16x32_bf16 v[80:83], v[176:179], v[224:227], v[80:83]
	v_mfma_f32_16x16x32_bf16 v[68:71], v[168:171], v[232:235], v[68:71]
	v_mfma_f32_16x16x32_bf16 v[64:67], v[176:179], v[232:235], v[64:67]
	s_setprio 0
	s_barrier
	s_add_i32 s68, s68, s34
	v_lshl_add_u64 v[142:143], s[66:67], 0, v[130:131]
	s_mov_b32 m0, s68
	ds_read_b128 v[180:183], v147 offset:16384
	ds_read_b128 v[208:211], v147 offset:17408
	ds_read_b128 v[212:215], v147 offset:18432
	ds_read_b128 v[216:219], v147 offset:19456
	ds_read_b128 v[220:223], v147 offset:20480
	ds_read_b128 v[224:227], v147 offset:21504
	ds_read_b128 v[228:231], v147 offset:22528
	ds_read_b128 v[232:235], v147 offset:23552
	global_load_lds_dwordx4 v[142:143], off
	s_add_i32 m0, s68, 0x2000
	s_add_u32 s66, s66, s10
	v_lshl_add_u64 v[190:191], v[142:143], 0, s[8:9]
	s_addc_u32 s67, s67, s11
	s_add_i32 s4, s4, s34
	global_load_lds_dwordx4 v[190:191], off
	v_lshl_add_u64 v[192:193], s[66:67], 0, v[130:131]
	s_mov_b32 m0, s4
	v_lshl_add_u64 v[236:237], v[192:193], 0, s[8:9]
	global_load_lds_dwordx4 v[192:193], off
	s_add_i32 m0, s4, 0x2000
	v_lshl_add_u64 v[238:239], s[16:17], 0, v[136:137]
	global_load_lds_dwordx4 v[236:237], off
	s_mov_b32 m0, s35
	v_lshl_add_u64 v[240:241], v[238:239], 0, s[8:9]
	global_load_lds_dwordx4 v[238:239], off
	s_mov_b32 m0, s36
	s_nop 0
	global_load_lds_dwordx4 v[240:241], off
	s_waitcnt vmcnt(8)
	s_waitcnt lgkmcnt(0)
	s_barrier
; #define PG8_STAGE(bufoff, gbase, voff) do { _Pragma("unroll") for (int _i = 0; _i < 2; ++_i) \
;         __builtin_amdgcn_global_load_lds((const unsigned*)((const char*)(gbase) + _i * rdelta + (voff)), (LAS unsigned*)(lds + (bufoff) + ldsw + _i * 8192), 16, 0, 0); } while (0)
; #define PG8_LDA(dst, b, h) do { _Pragma("unroll") for (int m = 0; m < 4; ++m) _Pragma("unroll") for (int k = 0; k < 2; ++k) dst[m][k] = *(const LAS bf16x8*)(lds + PG8_SA(b, h) + aoff + m * 2048 + k * 1024); } while (0)
; #define PG8_LDB(dst, b, h) do { _Pragma("unroll") for (int n = 0; n < 2; ++n) _Pragma("unroll") for (int k = 0; k < 2; ++k) dst[n][k] = *(const LAS bf16x8*)(lds + PG8_SB(b, h) + boff + n * 2048 + k * 1024); } while (0)
; #define PG8_MMA(ai, bj, At, Bt) do { __builtin_amdgcn_s_setprio(1); _Pragma("unroll") for (int m = 0; m < 4; ++m) _Pragma("unroll") for (int n = 0; n < 2; ++n) _Pragma("unroll") for (int k = 0; k < 2; ++k) \
;         acc[ai][bj][m][n] = __builtin_amdgcn_mfma_f32_16x16x32_bf16(Bt[n][k], At[m][k], acc[ai][bj][m][n], 0, 0, 0); __builtin_amdgcn_s_setprio(0); } while (0)
; #define PG8_WAIT_V(n) asm volatile("s_waitcnt vmcnt(" #n ")" ::: "memory")
; #define PG8_WAIT_L(n) asm volatile("s_waitcnt lgkmcnt(" #n ")" ::: "memory")
; #define PG8_BAR __builtin_amdgcn_s_barrier()
; #define PG8_SCHED __builtin_amdgcn_sched_barrier(0)
; template <class Epi, class Sched, bool ALIGN_EPI, bool SP2>
; __device__ __forceinline__ void gemm_phase(LAS unsigned char* lds, const Gemm g, const Sched& S, const Epi& E) {
;     ...
;             PG8_WAIT_V(8); PG8_WAIT_L(0); PG8_BAR; PG8_MMA(1, 0, At, B0); PG8_MMA(1, 1, At, B1); PG8_BAR; PG8_SCHED;
;             PG8_LDB(B0, 1, 0); PG8_LDB(B1, 1, 1); PG8_SCHED; PG8_LDA(At, 1, 0); PG8_STAGE(PG8_SA(0, 1), a2 + hstep, voffA);
;             PG8_WAIT_V(8); PG8_WAIT_L(0); PG8_BAR; PG8_MMA(0, 0, At, B0); PG8_MMA(0, 1, At, B1); PG8_BAR; PG8_SCHED;
	s_setprio 1
	s_waitcnt lgkmcnt(0)
	v_mfma_f32_16x16x32_bf16 v[60:63], v[148:151], v[180:183], v[60:63]
	v_mfma_f32_16x16x32_bf16 v[56:59], v[156:159], v[180:183], v[56:59]
	v_mfma_f32_16x16x32_bf16 v[44:47], v[148:151], v[212:215], v[44:47]
	v_mfma_f32_16x16x32_bf16 v[40:43], v[156:159], v[212:215], v[40:43]
	v_mfma_f32_16x16x32_bf16 v[28:31], v[148:151], v[220:223], v[28:31]
	v_mfma_f32_16x16x32_bf16 v[24:27], v[156:159], v[220:223], v[24:27]
	v_mfma_f32_16x16x32_bf16 v[12:15], v[148:151], v[228:231], v[12:15]
	v_mfma_f32_16x16x32_bf16 v[8:11], v[156:159], v[228:231], v[8:11]
	v_mfma_f32_16x16x32_bf16 v[60:63], v[152:155], v[208:211], v[60:63]
	v_mfma_f32_16x16x32_bf16 v[56:59], v[160:163], v[208:211], v[56:59]
	v_mfma_f32_16x16x32_bf16 v[44:47], v[152:155], v[216:219], v[44:47]
	v_mfma_f32_16x16x32_bf16 v[40:43], v[160:163], v[216:219], v[40:43]
	v_mfma_f32_16x16x32_bf16 v[28:31], v[152:155], v[224:227], v[28:31]
	v_mfma_f32_16x16x32_bf16 v[24:27], v[160:163], v[224:227], v[24:27]
	v_mfma_f32_16x16x32_bf16 v[12:15], v[152:155], v[232:235], v[12:15]
	v_mfma_f32_16x16x32_bf16 v[8:11], v[160:163], v[232:235], v[8:11]
	s_setprio 0
	s_setprio 1
	v_mfma_f32_16x16x32_bf16 v[52:55], v[164:167], v[180:183], v[52:55]
	v_mfma_f32_16x16x32_bf16 v[48:51], v[172:175], v[180:183], v[48:51]
	v_mfma_f32_16x16x32_bf16 v[36:39], v[164:167], v[212:215], v[36:39]
	v_mfma_f32_16x16x32_bf16 v[32:35], v[172:175], v[212:215], v[32:35]
	v_mfma_f32_16x16x32_bf16 v[20:23], v[164:167], v[220:223], v[20:23]
	v_mfma_f32_16x16x32_bf16 v[16:19], v[172:175], v[220:223], v[16:19]
	v_mfma_f32_16x16x32_bf16 v[4:7], v[164:167], v[228:231], v[4:7]
	v_mfma_f32_16x16x32_bf16 v[0:3], v[172:175], v[228:231], v[0:3]
	v_mfma_f32_16x16x32_bf16 v[52:55], v[168:171], v[208:211], v[52:55]
	v_mfma_f32_16x16x32_bf16 v[48:51], v[176:179], v[208:211], v[48:51]
	v_mfma_f32_16x16x32_bf16 v[36:39], v[168:171], v[216:219], v[36:39]
	v_mfma_f32_16x16x32_bf16 v[32:35], v[176:179], v[216:219], v[32:35]
	v_mfma_f32_16x16x32_bf16 v[20:23], v[168:171], v[224:227], v[20:23]
	v_mfma_f32_16x16x32_bf16 v[16:19], v[176:179], v[224:227], v[16:19]
	v_mfma_f32_16x16x32_bf16 v[4:7], v[168:171], v[232:235], v[4:7]
	v_mfma_f32_16x16x32_bf16 v[0:3], v[176:179], v[232:235], v[0:3]
	s_setprio 0
	s_barrier
	s_add_i32 s4, 0, 0x18000
	v_add_u32_e32 v128, s4, v145
	s_add_i32 s66, 0, 0x1c000
	ds_read_b128 v[148:151], v128
	ds_read_b128 v[152:155], v128 offset:1024
	ds_read_b128 v[156:159], v128 offset:2048
	ds_read_b128 v[160:163], v128 offset:3072
	v_add_u32_e32 v128, s66, v145
	ds_read_b128 v[164:167], v128
	ds_read_b128 v[168:171], v128 offset:1024
	ds_read_b128 v[172:175], v128 offset:2048
	ds_read_b128 v[176:179], v128 offset:3072
	s_add_u32 s16, s16, s10
	s_addc_u32 s17, s17, s11
	s_mov_b32 m0, s37
	v_lshl_add_u64 v[242:243], s[16:17], 0, v[136:137]
	ds_read_b128 v[180:183], v147 offset:32768
	ds_read_b128 v[208:211], v147 offset:33792
	ds_read_b128 v[212:215], v147 offset:34816
	ds_read_b128 v[216:219], v147 offset:35840
	ds_read_b128 v[220:223], v147 offset:36864
	ds_read_b128 v[224:227], v147 offset:37888
	ds_read_b128 v[228:231], v147 offset:38912
	ds_read_b128 v[232:235], v147 offset:39936
	global_load_lds_dwordx4 v[242:243], off
	v_lshl_add_u64 v[242:243], v[242:243], 0, s[8:9]
	s_mov_b32 m0, s38
	s_nop 0
	global_load_lds_dwordx4 v[242:243], off
	s_waitcnt vmcnt(8)
	s_waitcnt lgkmcnt(0)
	s_barrier
	s_setprio 1
	s_waitcnt lgkmcnt(0)
	v_mfma_f32_16x16x32_bf16 v[120:123], v[148:151], v[180:183], v[120:123]
	v_mfma_f32_16x16x32_bf16 v[124:127], v[156:159], v[180:183], v[124:127]
	v_mfma_f32_16x16x32_bf16 v[108:111], v[148:151], v[212:215], v[108:111]
	v_mfma_f32_16x16x32_bf16 v[104:107], v[156:159], v[212:215], v[104:107]
	v_mfma_f32_16x16x32_bf16 v[92:95], v[148:151], v[220:223], v[92:95]
	v_mfma_f32_16x16x32_bf16 v[88:91], v[156:159], v[220:223], v[88:91]
	v_mfma_f32_16x16x32_bf16 v[76:79], v[148:151], v[228:231], v[76:79]
	v_mfma_f32_16x16x32_bf16 v[72:75], v[156:159], v[228:231], v[72:75]
	v_mfma_f32_16x16x32_bf16 v[120:123], v[152:155], v[208:211], v[120:123]
	v_mfma_f32_16x16x32_bf16 v[124:127], v[160:163], v[208:211], v[124:127]
	v_mfma_f32_16x16x32_bf16 v[108:111], v[152:155], v[216:219], v[108:111]
	v_mfma_f32_16x16x32_bf16 v[104:107], v[160:163], v[216:219], v[104:107]
	v_mfma_f32_16x16x32_bf16 v[92:95], v[152:155], v[224:227], v[92:95]
	v_mfma_f32_16x16x32_bf16 v[88:91], v[160:163], v[224:227], v[88:91]
	v_mfma_f32_16x16x32_bf16 v[76:79], v[152:155], v[232:235], v[76:79]
	v_mfma_f32_16x16x32_bf16 v[72:75], v[160:163], v[232:235], v[72:75]
	s_setprio 0
	s_setprio 1
	v_mfma_f32_16x16x32_bf16 v[116:119], v[164:167], v[180:183], v[116:119]
	v_mfma_f32_16x16x32_bf16 v[112:115], v[172:175], v[180:183], v[112:115]
	v_mfma_f32_16x16x32_bf16 v[100:103], v[164:167], v[212:215], v[100:103]
	v_mfma_f32_16x16x32_bf16 v[96:99], v[172:175], v[212:215], v[96:99]
	v_mfma_f32_16x16x32_bf16 v[84:87], v[164:167], v[220:223], v[84:87]
	v_mfma_f32_16x16x32_bf16 v[80:83], v[172:175], v[220:223], v[80:83]
	v_mfma_f32_16x16x32_bf16 v[68:71], v[164:167], v[228:231], v[68:71]
	v_mfma_f32_16x16x32_bf16 v[64:67], v[172:175], v[228:231], v[64:67]
	v_mfma_f32_16x16x32_bf16 v[116:119], v[168:171], v[208:211], v[116:119]
	v_mfma_f32_16x16x32_bf16 v[112:115], v[176:179], v[208:211], v[112:115]
	v_mfma_f32_16x16x32_bf16 v[100:103], v[168:171], v[216:219], v[100:103]
	v_mfma_f32_16x16x32_bf16 v[96:99], v[176:179], v[216:219], v[96:99]
	v_mfma_f32_16x16x32_bf16 v[84:87], v[168:171], v[224:227], v[84:87]
	v_mfma_f32_16x16x32_bf16 v[80:83], v[176:179], v[224:227], v[80:83]
	v_mfma_f32_16x16x32_bf16 v[68:71], v[168:171], v[232:235], v[68:71]
	v_mfma_f32_16x16x32_bf16 v[64:67], v[176:179], v[232:235], v[64:67]
	s_setprio 0
	s_barrier
; #define PG8_STAGE(bufoff, gbase, voff) do { _Pragma("unroll") for (int _i = 0; _i < 2; ++_i) \
;         __builtin_amdgcn_global_load_lds((const unsigned*)((const char*)(gbase) + _i * rdelta + (voff)), (LAS unsigned*)(lds + (bufoff) + ldsw + _i * 8192), 16, 0, 0); } while (0)
; #define PG8_LDA(dst, b, h) do { _Pragma("unroll") for (int m = 0; m < 4; ++m) _Pragma("unroll") for (int k = 0; k < 2; ++k) dst[m][k] = *(const LAS bf16x8*)(lds + PG8_SA(b, h) + aoff + m * 2048 + k * 1024); } while (0)
; #define PG8_MMA(ai, bj, At, Bt) do { __builtin_amdgcn_s_setprio(1); _Pragma("unroll") for (int m = 0; m < 4; ++m) _Pragma("unroll") for (int n = 0; n < 2; ++n) _Pragma("unroll") for (int k = 0; k < 2; ++k) \
;         acc[ai][bj][m][n] = __builtin_amdgcn_mfma_f32_16x16x32_bf16(Bt[n][k], At[m][k], acc[ai][bj][m][n], 0, 0, 0); __builtin_amdgcn_s_setprio(0); } while (0)
; #define PG8_WAIT_V(n) asm volatile("s_waitcnt vmcnt(" #n ")" ::: "memory")
; #define PG8_WAIT_L(n) asm volatile("s_waitcnt lgkmcnt(" #n ")" ::: "memory")
; #define PG8_BAR __builtin_amdgcn_s_barrier()
; #define PG8_SCHED __builtin_amdgcn_sched_barrier(0)
; template <class Epi, class Sched, bool ALIGN_EPI, bool SP2>
; __device__ __forceinline__ void gemm_phase(LAS unsigned char* lds, const Gemm g, const Sched& S, const Epi& E) {
;     ...
;             PG8_LDA(At, 1, 1); PG8_STAGE(PG8_SB(1, 0), b3, voffB); PG8_STAGE(PG8_SB(1, 1), b3 + hstep, voffB); PG8_STAGE(PG8_SA(1, 0), a3, voffA);
;             PG8_WAIT_V(8); PG8_WAIT_L(0); PG8_BAR; PG8_MMA(1, 0, At, B0); PG8_MMA(1, 1, At, B1); PG8_BAR; PG8_SCHED;
;         }
	s_add_i32 s4, s4, s34
	v_lshl_add_u64 v[142:143], v[142:143], 0, s[30:31]
	s_mov_b32 m0, s4
	ds_read_b128 v[180:183], v147 offset:49152
	ds_read_b128 v[208:211], v147 offset:50176
	ds_read_b128 v[212:215], v147 offset:51200
	ds_read_b128 v[216:219], v147 offset:52224
	ds_read_b128 v[220:223], v147 offset:53248
	ds_read_b128 v[224:227], v147 offset:54272
	ds_read_b128 v[228:231], v147 offset:55296
	ds_read_b128 v[232:235], v147 offset:56320
	global_load_lds_dwordx4 v[142:143], off
	v_lshl_add_u64 v[142:143], v[190:191], 0, s[30:31]
	s_add_i32 m0, s4, 0x2000
	s_add_i32 s4, s66, s34
	global_load_lds_dwordx4 v[142:143], off
	v_lshl_add_u64 v[142:143], v[192:193], 0, s[30:31]
	s_mov_b32 m0, s4
	s_nop 0
	global_load_lds_dwordx4 v[142:143], off
	v_lshl_add_u64 v[142:143], v[236:237], 0, s[30:31]
	s_add_i32 m0, s4, 0x2000
	s_nop 0
	global_load_lds_dwordx4 v[142:143], off
	v_lshl_add_u64 v[142:143], v[238:239], 0, s[30:31]
	s_mov_b32 m0, s58
	s_nop 0
	global_load_lds_dwordx4 v[142:143], off
	v_lshl_add_u64 v[142:143], v[240:241], 0, s[30:31]
	s_mov_b32 m0, s59
	s_nop 0
	global_load_lds_dwordx4 v[142:143], off
	s_waitcnt vmcnt(8)
	s_waitcnt lgkmcnt(0)
	s_barrier
	s_setprio 1
	s_waitcnt lgkmcnt(0)
	v_mfma_f32_16x16x32_bf16 v[60:63], v[148:151], v[180:183], v[60:63]
	v_mfma_f32_16x16x32_bf16 v[56:59], v[156:159], v[180:183], v[56:59]
	v_mfma_f32_16x16x32_bf16 v[44:47], v[148:151], v[212:215], v[44:47]
	v_mfma_f32_16x16x32_bf16 v[40:43], v[156:159], v[212:215], v[40:43]
	v_mfma_f32_16x16x32_bf16 v[28:31], v[148:151], v[220:223], v[28:31]
	v_mfma_f32_16x16x32_bf16 v[24:27], v[156:159], v[220:223], v[24:27]
	v_mfma_f32_16x16x32_bf16 v[12:15], v[148:151], v[228:231], v[12:15]
	v_mfma_f32_16x16x32_bf16 v[8:11], v[156:159], v[228:231], v[8:11]
	v_mfma_f32_16x16x32_bf16 v[60:63], v[152:155], v[208:211], v[60:63]
	v_mfma_f32_16x16x32_bf16 v[56:59], v[160:163], v[208:211], v[56:59]
	v_mfma_f32_16x16x32_bf16 v[44:47], v[152:155], v[216:219], v[44:47]
	v_mfma_f32_16x16x32_bf16 v[40:43], v[160:163], v[216:219], v[40:43]
	v_mfma_f32_16x16x32_bf16 v[28:31], v[152:155], v[224:227], v[28:31]
	v_mfma_f32_16x16x32_bf16 v[24:27], v[160:163], v[224:227], v[24:27]
	v_mfma_f32_16x16x32_bf16 v[12:15], v[152:155], v[232:235], v[12:15]
	v_mfma_f32_16x16x32_bf16 v[8:11], v[160:163], v[232:235], v[8:11]
	s_setprio 0
	s_setprio 1
	v_mfma_f32_16x16x32_bf16 v[52:55], v[164:167], v[180:183], v[52:55]
	v_mfma_f32_16x16x32_bf16 v[48:51], v[172:175], v[180:183], v[48:51]
	v_mfma_f32_16x16x32_bf16 v[36:39], v[164:167], v[212:215], v[36:39]
	v_mfma_f32_16x16x32_bf16 v[32:35], v[172:175], v[212:215], v[32:35]
	v_mfma_f32_16x16x32_bf16 v[20:23], v[164:167], v[220:223], v[20:23]
	v_mfma_f32_16x16x32_bf16 v[16:19], v[172:175], v[220:223], v[16:19]
	v_mfma_f32_16x16x32_bf16 v[4:7], v[164:167], v[228:231], v[4:7]
	v_mfma_f32_16x16x32_bf16 v[0:3], v[172:175], v[228:231], v[0:3]
	v_mfma_f32_16x16x32_bf16 v[52:55], v[168:171], v[208:211], v[52:55]
	v_mfma_f32_16x16x32_bf16 v[48:51], v[176:179], v[208:211], v[48:51]
	v_mfma_f32_16x16x32_bf16 v[36:39], v[168:171], v[216:219], v[36:39]
	v_mfma_f32_16x16x32_bf16 v[32:35], v[176:179], v[216:219], v[32:35]
	v_mfma_f32_16x16x32_bf16 v[20:23], v[168:171], v[224:227], v[20:23]
	v_mfma_f32_16x16x32_bf16 v[16:19], v[176:179], v[224:227], v[16:19]
	v_mfma_f32_16x16x32_bf16 v[4:7], v[168:171], v[232:235], v[4:7]
	v_mfma_f32_16x16x32_bf16 v[0:3], v[176:179], v[232:235], v[0:3]
	s_setprio 0
	s_add_u32 s14, s14, 0x100
	s_addc_u32 s15, s15, 0
	s_add_u32 s18, s18, 0x100
	s_addc_u32 s19, s19, 0
	s_cmp_ge_i32 s65, s60
	s_mov_b32 s4, s65
	s_barrier
	s_cbranch_scc0 .LBB0_1365

; #define PG8_STAGE(bufoff, gbase, voff) do { _Pragma("unroll") for (int _i = 0; _i < 2; ++_i) \
;         __builtin_amdgcn_global_load_lds((const unsigned*)((const char*)(gbase) + _i * rdelta + (voff)), (LAS unsigned*)(lds + (bufoff) + ldsw + _i * 8192), 16, 0, 0); } while (0)
; #define PG8_LDA(dst, b, h) do { _Pragma("unroll") for (int m = 0; m < 4; ++m) _Pragma("unroll") for (int k = 0; k < 2; ++k) dst[m][k] = *(const LAS bf16x8*)(lds + PG8_SA(b, h) + aoff + m * 2048 + k * 1024); } while (0)
; #define PG8_LDB(dst, b, h) do { _Pragma("unroll") for (int n = 0; n < 2; ++n) _Pragma("unroll") for (int k = 0; k < 2; ++k) dst[n][k] = *(const LAS bf16x8*)(lds + PG8_SB(b, h) + boff + n * 2048 + k * 1024); } while (0)
; #define PG8_MMA(ai, bj, At, Bt) do { __builtin_amdgcn_s_setprio(1); _Pragma("unroll") for (int m = 0; m < 4; ++m) _Pragma("unroll") for (int n = 0; n < 2; ++n) _Pragma("unroll") for (int k = 0; k < 2; ++k) \
;         acc[ai][bj][m][n] = __builtin_amdgcn_mfma_f32_16x16x32_bf16(Bt[n][k], At[m][k], acc[ai][bj][m][n], 0, 0, 0); __builtin_amdgcn_s_setprio(0); } while (0)
; #define PG8_WAIT_V(n) asm volatile("s_waitcnt vmcnt(" #n ")" ::: "memory")
; #define PG8_WAIT_L(n) asm volatile("s_waitcnt lgkmcnt(" #n ")" ::: "memory")
; template <class Epi, class Sched, bool ALIGN_EPI, bool SP2>
; __device__ __forceinline__ void gemm_phase(LAS unsigned char* lds, const Gemm g, const Sched& S, const Epi& E) {
;     ...
;         for (int t = 0; t < nt; t += 2) {
;             if constexpr (Epi::HOOK) { if (t == Epi::T1 || t == Epi::T2) E.hook(acc, ui, t, wr, fr); }
;             const bool last = (t == nt - 2);
;             const char* a1 = cA + (size_t)(t + 1) * kstep;
;             const char* a2 = last ? nA : cA + (size_t)(t + 2) * kstep; const char* b2 = last ? nB : cB + (size_t)(t + 2) * kstep;
;             const char* a3 = a2 + kstep; const char* b3 = b2 + kstep;
;             PG8_LDB(B0, 0, 0); PG8_LDB(B1, 0, 1); PG8_SCHED; PG8_LDA(At, 0, 0); PG8_STAGE(PG8_SA(1, 1), a1 + hstep, voffA);
;             PG8_WAIT_V(8); PG8_WAIT_L(0); PG8_BAR; PG8_MMA(0, 0, At, B0); PG8_MMA(0, 1, At, B1); PG8_BAR; PG8_SCHED;
;             PG8_LDA(At, 0, 1); PG8_STAGE(PG8_SB(0, 0), b2, voffB); PG8_STAGE(PG8_SB(0, 1), b2 + hstep, voffB); PG8_STAGE(PG8_SA(0, 0), a2, voffA);
;             PG8_WAIT_V(8); PG8_WAIT_L(0); PG8_BAR; PG8_MMA(1, 0, At, B0); PG8_MMA(1, 1, At, B1); PG8_BAR; PG8_SCHED;
.LBB0_1564:
	s_add_i32 s67, s4, 2
	s_add_u32 s16, s14, 0x80
	s_addc_u32 s17, s15, 0
	s_add_i32 s70, 0, 0x10000
	s_cmp_eq_u32 s61, s4
	s_cselect_b32 s17, s7, s17
	s_cselect_b32 s16, s6, s16
	s_cselect_b32 s69, s59, s19
	s_cselect_b32 s68, s58, s18
	s_add_i32 s4, 0, 0x14000
	v_add_u32_e32 v156, s70, v146
	v_add_u32_e32 v172, s4, v146
	ds_read_b128 v[142:145], v156
	ds_read_b128 v[148:151], v156 offset:1024
	ds_read_b128 v[152:155], v156 offset:2048
	ds_read_b128 v[156:159], v156 offset:3072
	ds_read_b128 v[160:163], v172
	ds_read_b128 v[164:167], v172 offset:1024
	ds_read_b128 v[168:171], v172 offset:2048
	ds_read_b128 v[172:175], v172 offset:3072
	v_lshl_add_u64 v[190:191], s[14:15], 0, v[138:139]
	s_add_i32 m0, s35, 0xc000
	ds_read_b128 v[176:179], v147
	ds_read_b128 v[180:183], v147 offset:1024
	ds_read_b128 v[208:211], v147 offset:2048
	ds_read_b128 v[212:215], v147 offset:3072
	ds_read_b128 v[216:219], v147 offset:4096
	ds_read_b128 v[220:223], v147 offset:5120
	ds_read_b128 v[224:227], v147 offset:6144
	ds_read_b128 v[228:231], v147 offset:7168
	global_load_lds_dwordx4 v[190:191], off
	v_lshl_add_u64 v[190:191], s[14:15], 0, v[140:141]
	s_add_i32 m0, s35, 0xe000
	s_nop 0
	global_load_lds_dwordx4 v[190:191], off
	s_waitcnt vmcnt(8)
	s_waitcnt lgkmcnt(0)
	s_barrier
	s_setprio 1
	s_waitcnt lgkmcnt(0)
	v_mfma_f32_16x16x32_bf16 v[120:123], v[142:145], v[176:179], v[120:123]
	v_mfma_f32_16x16x32_bf16 v[124:127], v[152:155], v[176:179], v[124:127]
	v_mfma_f32_16x16x32_bf16 v[108:111], v[142:145], v[208:211], v[108:111]
	v_mfma_f32_16x16x32_bf16 v[104:107], v[152:155], v[208:211], v[104:107]
	v_mfma_f32_16x16x32_bf16 v[92:95], v[142:145], v[216:219], v[92:95]
	v_mfma_f32_16x16x32_bf16 v[88:91], v[152:155], v[216:219], v[88:91]
	v_mfma_f32_16x16x32_bf16 v[76:79], v[142:145], v[224:227], v[76:79]
	v_mfma_f32_16x16x32_bf16 v[72:75], v[152:155], v[224:227], v[72:75]
	v_mfma_f32_16x16x32_bf16 v[120:123], v[148:151], v[180:183], v[120:123]
	v_mfma_f32_16x16x32_bf16 v[124:127], v[156:159], v[180:183], v[124:127]
	v_mfma_f32_16x16x32_bf16 v[108:111], v[148:151], v[212:215], v[108:111]
	v_mfma_f32_16x16x32_bf16 v[104:107], v[156:159], v[212:215], v[104:107]
	v_mfma_f32_16x16x32_bf16 v[92:95], v[148:151], v[220:223], v[92:95]
	v_mfma_f32_16x16x32_bf16 v[88:91], v[156:159], v[220:223], v[88:91]
	v_mfma_f32_16x16x32_bf16 v[76:79], v[148:151], v[228:231], v[76:79]
	v_mfma_f32_16x16x32_bf16 v[72:75], v[156:159], v[228:231], v[72:75]
	s_setprio 0
	s_setprio 1
	v_mfma_f32_16x16x32_bf16 v[116:119], v[160:163], v[176:179], v[116:119]
	v_mfma_f32_16x16x32_bf16 v[112:115], v[168:171], v[176:179], v[112:115]
	v_mfma_f32_16x16x32_bf16 v[100:103], v[160:163], v[208:211], v[100:103]
	v_mfma_f32_16x16x32_bf16 v[96:99], v[168:171], v[208:211], v[96:99]
	v_mfma_f32_16x16x32_bf16 v[84:87], v[160:163], v[216:219], v[84:87]
	v_mfma_f32_16x16x32_bf16 v[80:83], v[168:171], v[216:219], v[80:83]
	v_mfma_f32_16x16x32_bf16 v[68:71], v[160:163], v[224:227], v[68:71]
	v_mfma_f32_16x16x32_bf16 v[64:67], v[168:171], v[224:227], v[64:67]
	v_mfma_f32_16x16x32_bf16 v[116:119], v[164:167], v[180:183], v[116:119]
	v_mfma_f32_16x16x32_bf16 v[112:115], v[172:175], v[180:183], v[112:115]
	v_mfma_f32_16x16x32_bf16 v[100:103], v[164:167], v[212:215], v[100:103]
	v_mfma_f32_16x16x32_bf16 v[96:99], v[172:175], v[212:215], v[96:99]
	v_mfma_f32_16x16x32_bf16 v[84:87], v[164:167], v[220:223], v[84:87]
	v_mfma_f32_16x16x32_bf16 v[80:83], v[172:175], v[220:223], v[80:83]
	v_mfma_f32_16x16x32_bf16 v[68:71], v[164:167], v[228:231], v[68:71]
	v_mfma_f32_16x16x32_bf16 v[64:67], v[172:175], v[228:231], v[64:67]
	s_setprio 0
	s_barrier
	s_add_i32 s70, s70, s34
	v_lshl_add_u64 v[190:191], s[68:69], 0, v[128:129]
	s_mov_b32 m0, s70
	ds_read_b128 v[176:179], v147 offset:16384
	ds_read_b128 v[180:183], v147 offset:17408
	ds_read_b128 v[208:211], v147 offset:18432
	ds_read_b128 v[212:215], v147 offset:19456
	ds_read_b128 v[216:219], v147 offset:20480
	ds_read_b128 v[220:223], v147 offset:21504
	ds_read_b128 v[224:227], v147 offset:22528
	ds_read_b128 v[228:231], v147 offset:23552
	global_load_lds_dwordx4 v[190:191], off
	s_add_i32 m0, s70, 0x2000
	s_add_u32 s68, s68, s10
	v_lshl_add_u64 v[192:193], v[190:191], 0, s[8:9]
	s_addc_u32 s69, s69, s11
	s_add_i32 s4, s4, s34
	global_load_lds_dwordx4 v[192:193], off
	v_lshl_add_u64 v[232:233], s[68:69], 0, v[128:129]
	s_mov_b32 m0, s4
	v_lshl_add_u64 v[234:235], v[232:233], 0, s[8:9]
	global_load_lds_dwordx4 v[232:233], off
	s_add_i32 m0, s4, 0x2000
	v_lshl_add_u64 v[236:237], s[16:17], 0, v[130:131]
	global_load_lds_dwordx4 v[234:235], off
	s_mov_b32 m0, s35
	v_lshl_add_u64 v[238:239], v[236:237], 0, s[8:9]
	global_load_lds_dwordx4 v[236:237], off
	s_mov_b32 m0, s36
	s_nop 0
	global_load_lds_dwordx4 v[238:239], off
	s_waitcnt vmcnt(8)
	s_waitcnt lgkmcnt(0)
	s_barrier
; #define PG8_STAGE(bufoff, gbase, voff) do { _Pragma("unroll") for (int _i = 0; _i < 2; ++_i) \
;         __builtin_amdgcn_global_load_lds((const unsigned*)((const char*)(gbase) + _i * rdelta + (voff)), (LAS unsigned*)(lds + (bufoff) + ldsw + _i * 8192), 16, 0, 0); } while (0)
; #define PG8_LDA(dst, b, h) do { _Pragma("unroll") for (int m = 0; m < 4; ++m) _Pragma("unroll") for (int k = 0; k < 2; ++k) dst[m][k] = *(const LAS bf16x8*)(lds + PG8_SA(b, h) + aoff + m * 2048 + k * 1024); } while (0)
; #define PG8_LDB(dst, b, h) do { _Pragma("unroll") for (int n = 0; n < 2; ++n) _Pragma("unroll") for (int k = 0; k < 2; ++k) dst[n][k] = *(const LAS bf16x8*)(lds + PG8_SB(b, h) + boff + n * 2048 + k * 1024); } while (0)
; #define PG8_MMA(ai, bj, At, Bt) do { __builtin_amdgcn_s_setprio(1); _Pragma("unroll") for (int m = 0; m < 4; ++m) _Pragma("unroll") for (int n = 0; n < 2; ++n) _Pragma("unroll") for (int k = 0; k < 2; ++k) \
;         acc[ai][bj][m][n] = __builtin_amdgcn_mfma_f32_16x16x32_bf16(Bt[n][k], At[m][k], acc[ai][bj][m][n], 0, 0, 0); __builtin_amdgcn_s_setprio(0); } while (0)
; #define PG8_WAIT_V(n) asm volatile("s_waitcnt vmcnt(" #n ")" ::: "memory")
; #define PG8_WAIT_L(n) asm volatile("s_waitcnt lgkmcnt(" #n ")" ::: "memory")
; #define PG8_BAR __builtin_amdgcn_s_barrier()
; #define PG8_SCHED __builtin_amdgcn_sched_barrier(0)
; template <class Epi, class Sched, bool ALIGN_EPI, bool SP2>
; __device__ __forceinline__ void gemm_phase(LAS unsigned char* lds, const Gemm g, const Sched& S, const Epi& E) {
;     ...
;             PG8_WAIT_V(8); PG8_WAIT_L(0); PG8_BAR; PG8_MMA(1, 0, At, B0); PG8_MMA(1, 1, At, B1); PG8_BAR; PG8_SCHED;
;             PG8_LDB(B0, 1, 0); PG8_LDB(B1, 1, 1); PG8_SCHED; PG8_LDA(At, 1, 0); PG8_STAGE(PG8_SA(0, 1), a2 + hstep, voffA);
;             PG8_WAIT_V(8); PG8_WAIT_L(0); PG8_BAR; PG8_MMA(0, 0, At, B0); PG8_MMA(0, 1, At, B1); PG8_BAR; PG8_SCHED;
	s_setprio 1
	s_waitcnt lgkmcnt(0)
	v_mfma_f32_16x16x32_bf16 v[60:63], v[142:145], v[176:179], v[60:63]
	v_mfma_f32_16x16x32_bf16 v[56:59], v[152:155], v[176:179], v[56:59]
	v_mfma_f32_16x16x32_bf16 v[44:47], v[142:145], v[208:211], v[44:47]
	v_mfma_f32_16x16x32_bf16 v[40:43], v[152:155], v[208:211], v[40:43]
	v_mfma_f32_16x16x32_bf16 v[28:31], v[142:145], v[216:219], v[28:31]
	v_mfma_f32_16x16x32_bf16 v[24:27], v[152:155], v[216:219], v[24:27]
	v_mfma_f32_16x16x32_bf16 v[12:15], v[142:145], v[224:227], v[12:15]
	v_mfma_f32_16x16x32_bf16 v[8:11], v[152:155], v[224:227], v[8:11]
	v_mfma_f32_16x16x32_bf16 v[60:63], v[148:151], v[180:183], v[60:63]
	v_mfma_f32_16x16x32_bf16 v[56:59], v[156:159], v[180:183], v[56:59]
	v_mfma_f32_16x16x32_bf16 v[44:47], v[148:151], v[212:215], v[44:47]
	v_mfma_f32_16x16x32_bf16 v[40:43], v[156:159], v[212:215], v[40:43]
	v_mfma_f32_16x16x32_bf16 v[28:31], v[148:151], v[220:223], v[28:31]
	v_mfma_f32_16x16x32_bf16 v[24:27], v[156:159], v[220:223], v[24:27]
	v_mfma_f32_16x16x32_bf16 v[12:15], v[148:151], v[228:231], v[12:15]
	v_mfma_f32_16x16x32_bf16 v[8:11], v[156:159], v[228:231], v[8:11]
	s_setprio 0
	s_setprio 1
	v_mfma_f32_16x16x32_bf16 v[52:55], v[160:163], v[176:179], v[52:55]
	v_mfma_f32_16x16x32_bf16 v[48:51], v[168:171], v[176:179], v[48:51]
	v_mfma_f32_16x16x32_bf16 v[36:39], v[160:163], v[208:211], v[36:39]
	v_mfma_f32_16x16x32_bf16 v[32:35], v[168:171], v[208:211], v[32:35]
	v_mfma_f32_16x16x32_bf16 v[20:23], v[160:163], v[216:219], v[20:23]
	v_mfma_f32_16x16x32_bf16 v[16:19], v[168:171], v[216:219], v[16:19]
	v_mfma_f32_16x16x32_bf16 v[4:7], v[160:163], v[224:227], v[4:7]
	v_mfma_f32_16x16x32_bf16 v[0:3], v[168:171], v[224:227], v[0:3]
	v_mfma_f32_16x16x32_bf16 v[52:55], v[164:167], v[180:183], v[52:55]
	v_mfma_f32_16x16x32_bf16 v[48:51], v[172:175], v[180:183], v[48:51]
	v_mfma_f32_16x16x32_bf16 v[36:39], v[164:167], v[212:215], v[36:39]
	v_mfma_f32_16x16x32_bf16 v[32:35], v[172:175], v[212:215], v[32:35]
	v_mfma_f32_16x16x32_bf16 v[20:23], v[164:167], v[220:223], v[20:23]
	v_mfma_f32_16x16x32_bf16 v[16:19], v[172:175], v[220:223], v[16:19]
	v_mfma_f32_16x16x32_bf16 v[4:7], v[164:167], v[228:231], v[4:7]
	v_mfma_f32_16x16x32_bf16 v[0:3], v[172:175], v[228:231], v[0:3]
	s_setprio 0
	s_barrier
	s_add_i32 s4, 0, 0x18000
	s_add_i32 s68, 0, 0x1c000
	v_add_u32_e32 v156, s4, v146
	v_add_u32_e32 v172, s68, v146
	ds_read_b128 v[142:145], v156
	ds_read_b128 v[148:151], v156 offset:1024
	ds_read_b128 v[152:155], v156 offset:2048
	ds_read_b128 v[156:159], v156 offset:3072
	ds_read_b128 v[160:163], v172
	ds_read_b128 v[164:167], v172 offset:1024
	ds_read_b128 v[168:171], v172 offset:2048
	ds_read_b128 v[172:175], v172 offset:3072
	s_add_u32 s16, s16, s10
	s_addc_u32 s17, s17, s11
	s_mov_b32 m0, s37
	v_lshl_add_u64 v[240:241], s[16:17], 0, v[130:131]
	ds_read_b128 v[176:179], v147 offset:32768
	ds_read_b128 v[180:183], v147 offset:33792
	ds_read_b128 v[208:211], v147 offset:34816
	ds_read_b128 v[212:215], v147 offset:35840
	ds_read_b128 v[216:219], v147 offset:36864
	ds_read_b128 v[220:223], v147 offset:37888
	ds_read_b128 v[224:227], v147 offset:38912
	ds_read_b128 v[228:231], v147 offset:39936
	global_load_lds_dwordx4 v[240:241], off
	v_lshl_add_u64 v[240:241], v[240:241], 0, s[8:9]
	s_mov_b32 m0, s40
	s_nop 0
	global_load_lds_dwordx4 v[240:241], off
	s_waitcnt vmcnt(8)
	s_waitcnt lgkmcnt(0)
	s_barrier
	s_setprio 1
	s_waitcnt lgkmcnt(0)
	v_mfma_f32_16x16x32_bf16 v[120:123], v[142:145], v[176:179], v[120:123]
	v_mfma_f32_16x16x32_bf16 v[124:127], v[152:155], v[176:179], v[124:127]
	v_mfma_f32_16x16x32_bf16 v[108:111], v[142:145], v[208:211], v[108:111]
	v_mfma_f32_16x16x32_bf16 v[104:107], v[152:155], v[208:211], v[104:107]
	v_mfma_f32_16x16x32_bf16 v[92:95], v[142:145], v[216:219], v[92:95]
	v_mfma_f32_16x16x32_bf16 v[88:91], v[152:155], v[216:219], v[88:91]
	v_mfma_f32_16x16x32_bf16 v[76:79], v[142:145], v[224:227], v[76:79]
	v_mfma_f32_16x16x32_bf16 v[72:75], v[152:155], v[224:227], v[72:75]
	v_mfma_f32_16x16x32_bf16 v[120:123], v[148:151], v[180:183], v[120:123]
	v_mfma_f32_16x16x32_bf16 v[124:127], v[156:159], v[180:183], v[124:127]
	v_mfma_f32_16x16x32_bf16 v[108:111], v[148:151], v[212:215], v[108:111]
	v_mfma_f32_16x16x32_bf16 v[104:107], v[156:159], v[212:215], v[104:107]
	v_mfma_f32_16x16x32_bf16 v[92:95], v[148:151], v[220:223], v[92:95]
	v_mfma_f32_16x16x32_bf16 v[88:91], v[156:159], v[220:223], v[88:91]
	v_mfma_f32_16x16x32_bf16 v[76:79], v[148:151], v[228:231], v[76:79]
	v_mfma_f32_16x16x32_bf16 v[72:75], v[156:159], v[228:231], v[72:75]
	s_setprio 0
	s_setprio 1
	v_mfma_f32_16x16x32_bf16 v[116:119], v[160:163], v[176:179], v[116:119]
	v_mfma_f32_16x16x32_bf16 v[112:115], v[168:171], v[176:179], v[112:115]
	v_mfma_f32_16x16x32_bf16 v[100:103], v[160:163], v[208:211], v[100:103]
	v_mfma_f32_16x16x32_bf16 v[96:99], v[168:171], v[208:211], v[96:99]
	v_mfma_f32_16x16x32_bf16 v[84:87], v[160:163], v[216:219], v[84:87]
	v_mfma_f32_16x16x32_bf16 v[80:83], v[168:171], v[216:219], v[80:83]
	v_mfma_f32_16x16x32_bf16 v[68:71], v[160:163], v[224:227], v[68:71]
	v_mfma_f32_16x16x32_bf16 v[64:67], v[168:171], v[224:227], v[64:67]
	v_mfma_f32_16x16x32_bf16 v[116:119], v[164:167], v[180:183], v[116:119]
	v_mfma_f32_16x16x32_bf16 v[112:115], v[172:175], v[180:183], v[112:115]
	v_mfma_f32_16x16x32_bf16 v[100:103], v[164:167], v[212:215], v[100:103]
	v_mfma_f32_16x16x32_bf16 v[96:99], v[172:175], v[212:215], v[96:99]
	v_mfma_f32_16x16x32_bf16 v[84:87], v[164:167], v[220:223], v[84:87]
	v_mfma_f32_16x16x32_bf16 v[80:83], v[172:175], v[220:223], v[80:83]
	v_mfma_f32_16x16x32_bf16 v[68:71], v[164:167], v[228:231], v[68:71]
	v_mfma_f32_16x16x32_bf16 v[64:67], v[172:175], v[228:231], v[64:67]
	s_setprio 0
	s_barrier
; #define PG8_STAGE(bufoff, gbase, voff) do { _Pragma("unroll") for (int _i = 0; _i < 2; ++_i) \
;         __builtin_amdgcn_global_load_lds((const unsigned*)((const char*)(gbase) + _i * rdelta + (voff)), (LAS unsigned*)(lds + (bufoff) + ldsw + _i * 8192), 16, 0, 0); } while (0)
; #define PG8_LDA(dst, b, h) do { _Pragma("unroll") for (int m = 0; m < 4; ++m) _Pragma("unroll") for (int k = 0; k < 2; ++k) dst[m][k] = *(const LAS bf16x8*)(lds + PG8_SA(b, h) + aoff + m * 2048 + k * 1024); } while (0)
; #define PG8_MMA(ai, bj, At, Bt) do { __builtin_amdgcn_s_setprio(1); _Pragma("unroll") for (int m = 0; m < 4; ++m) _Pragma("unroll") for (int n = 0; n < 2; ++n) _Pragma("unroll") for (int k = 0; k < 2; ++k) \
;         acc[ai][bj][m][n] = __builtin_amdgcn_mfma_f32_16x16x32_bf16(Bt[n][k], At[m][k], acc[ai][bj][m][n], 0, 0, 0); __builtin_amdgcn_s_setprio(0); } while (0)
; #define PG8_WAIT_V(n) asm volatile("s_waitcnt vmcnt(" #n ")" ::: "memory")
; #define PG8_WAIT_L(n) asm volatile("s_waitcnt lgkmcnt(" #n ")" ::: "memory")
; #define PG8_BAR __builtin_amdgcn_s_barrier()
; #define PG8_SCHED __builtin_amdgcn_sched_barrier(0)
; template <class Epi, class Sched, bool ALIGN_EPI, bool SP2>
; __device__ __forceinline__ void gemm_phase(LAS unsigned char* lds, const Gemm g, const Sched& S, const Epi& E) {
;     ...
;             PG8_LDA(At, 1, 1); PG8_STAGE(PG8_SB(1, 0), b3, voffB); PG8_STAGE(PG8_SB(1, 1), b3 + hstep, voffB); PG8_STAGE(PG8_SA(1, 0), a3, voffA);
;             PG8_WAIT_V(8); PG8_WAIT_L(0); PG8_BAR; PG8_MMA(1, 0, At, B0); PG8_MMA(1, 1, At, B1); PG8_BAR; PG8_SCHED;
;         }
	s_add_i32 s4, s4, s34
	v_lshl_add_u64 v[190:191], v[190:191], 0, s[30:31]
	s_mov_b32 m0, s4
	ds_read_b128 v[176:179], v147 offset:49152
	ds_read_b128 v[180:183], v147 offset:50176
	ds_read_b128 v[208:211], v147 offset:51200
	ds_read_b128 v[212:215], v147 offset:52224
	ds_read_b128 v[216:219], v147 offset:53248
	ds_read_b128 v[220:223], v147 offset:54272
	ds_read_b128 v[224:227], v147 offset:55296
	ds_read_b128 v[228:231], v147 offset:56320
	global_load_lds_dwordx4 v[190:191], off
	v_lshl_add_u64 v[190:191], v[192:193], 0, s[30:31]
	s_add_i32 m0, s4, 0x2000
	s_add_i32 s4, s68, s34
	global_load_lds_dwordx4 v[190:191], off
	v_lshl_add_u64 v[190:191], v[232:233], 0, s[30:31]
	s_mov_b32 m0, s4
	s_nop 0
	global_load_lds_dwordx4 v[190:191], off
	v_lshl_add_u64 v[190:191], v[234:235], 0, s[30:31]
	s_add_i32 m0, s4, 0x2000
	s_nop 0
	global_load_lds_dwordx4 v[190:191], off
	v_lshl_add_u64 v[190:191], v[236:237], 0, s[30:31]
	s_mov_b32 m0, s38
	s_nop 0
	global_load_lds_dwordx4 v[190:191], off
	v_lshl_add_u64 v[190:191], v[238:239], 0, s[30:31]
	s_mov_b32 m0, s41
	s_nop 0
	global_load_lds_dwordx4 v[190:191], off
	s_waitcnt vmcnt(8)
	s_waitcnt lgkmcnt(0)
	s_barrier
	s_setprio 1
	s_waitcnt lgkmcnt(0)
	v_mfma_f32_16x16x32_bf16 v[60:63], v[142:145], v[176:179], v[60:63]
	v_mfma_f32_16x16x32_bf16 v[56:59], v[152:155], v[176:179], v[56:59]
	v_mfma_f32_16x16x32_bf16 v[44:47], v[142:145], v[208:211], v[44:47]
	v_mfma_f32_16x16x32_bf16 v[40:43], v[152:155], v[208:211], v[40:43]
	v_mfma_f32_16x16x32_bf16 v[28:31], v[142:145], v[216:219], v[28:31]
	v_mfma_f32_16x16x32_bf16 v[24:27], v[152:155], v[216:219], v[24:27]
	v_mfma_f32_16x16x32_bf16 v[12:15], v[142:145], v[224:227], v[12:15]
	v_mfma_f32_16x16x32_bf16 v[8:11], v[152:155], v[224:227], v[8:11]
	v_mfma_f32_16x16x32_bf16 v[60:63], v[148:151], v[180:183], v[60:63]
	v_mfma_f32_16x16x32_bf16 v[56:59], v[156:159], v[180:183], v[56:59]
	v_mfma_f32_16x16x32_bf16 v[44:47], v[148:151], v[212:215], v[44:47]
	v_mfma_f32_16x16x32_bf16 v[40:43], v[156:159], v[212:215], v[40:43]
	v_mfma_f32_16x16x32_bf16 v[28:31], v[148:151], v[220:223], v[28:31]
	v_mfma_f32_16x16x32_bf16 v[24:27], v[156:159], v[220:223], v[24:27]
	v_mfma_f32_16x16x32_bf16 v[12:15], v[148:151], v[228:231], v[12:15]
	v_mfma_f32_16x16x32_bf16 v[8:11], v[156:159], v[228:231], v[8:11]
	s_setprio 0
	s_setprio 1
	v_mfma_f32_16x16x32_bf16 v[52:55], v[160:163], v[176:179], v[52:55]
	v_mfma_f32_16x16x32_bf16 v[48:51], v[168:171], v[176:179], v[48:51]
	v_mfma_f32_16x16x32_bf16 v[36:39], v[160:163], v[208:211], v[36:39]
	v_mfma_f32_16x16x32_bf16 v[32:35], v[168:171], v[208:211], v[32:35]
	v_mfma_f32_16x16x32_bf16 v[20:23], v[160:163], v[216:219], v[20:23]
	v_mfma_f32_16x16x32_bf16 v[16:19], v[168:171], v[216:219], v[16:19]
	v_mfma_f32_16x16x32_bf16 v[4:7], v[160:163], v[224:227], v[4:7]
	v_mfma_f32_16x16x32_bf16 v[0:3], v[168:171], v[224:227], v[0:3]
	v_mfma_f32_16x16x32_bf16 v[52:55], v[164:167], v[180:183], v[52:55]
	v_mfma_f32_16x16x32_bf16 v[48:51], v[172:175], v[180:183], v[48:51]
	v_mfma_f32_16x16x32_bf16 v[36:39], v[164:167], v[212:215], v[36:39]
	v_mfma_f32_16x16x32_bf16 v[32:35], v[172:175], v[212:215], v[32:35]
	v_mfma_f32_16x16x32_bf16 v[20:23], v[164:167], v[220:223], v[20:23]
	v_mfma_f32_16x16x32_bf16 v[16:19], v[172:175], v[220:223], v[16:19]
	v_mfma_f32_16x16x32_bf16 v[4:7], v[164:167], v[228:231], v[4:7]
	v_mfma_f32_16x16x32_bf16 v[0:3], v[172:175], v[228:231], v[0:3]
	s_setprio 0
	s_add_u32 s14, s14, 0x100
	s_addc_u32 s15, s15, 0
	s_add_u32 s18, s18, 0x100
	s_addc_u32 s19, s19, 0
	s_cmp_ge_i32 s67, s60
	s_mov_b32 s4, s67
	s_barrier
	s_cbranch_scc0 .LBB0_1564
